# no accumulator zero-init: first K-iteration of each GEMM unit peeled, first MFMA per accumulator takes srcC=0; stacks on v14
# speedup vs baseline: 1.0101x; 1.0012x over previous
;     __device__ __forceinline__ bool next(int i, Unit& u) const { if (!base.next(i >> 1, u)) return false; if (i & 1) { u.pm += 64; u.pn += 8; } return true; }
; #define PG8_STAGE(bufoff, gbase, voff) do { _Pragma("unroll") for (int _i = 0; _i < 2; ++_i) \
;         __builtin_amdgcn_global_load_lds((const unsigned*)((const char*)(gbase) + (voff)[_i]), (PG8_LAS unsigned*)(lds + (bufoff) + ldsw + _i * 8192), 16, 0, 0); } while (0)
; #define PG8_LDA(dst, b, h) do { _Pragma("unroll") for (int m = 0; m < 4; ++m) _Pragma("unroll") for (int k = 0; k < 2; ++k) dst[m][k] = *(const PG8_LAS bf16x8*)(lds + PG8_SA(b, h) + aoff + m * 2048 + k * 1024); } while (0)
; #define PG8_LDB(dst, b, h) do { _Pragma("unroll") for (int n = 0; n < 2; ++n) _Pragma("unroll") for (int k = 0; k < 2; ++k) dst[n][k] = *(const PG8_LAS bf16x8*)(lds + PG8_SB(b, h) + boff + n * 2048 + k * 1024); } while (0)
; #define PG8_WAIT_V(n) asm volatile("s_waitcnt vmcnt(" #n ")" ::: "memory")
; #define PG8_WAIT_L(n) asm volatile("s_waitcnt lgkmcnt(" #n ")" ::: "memory")
; #define PG8_BAR __builtin_amdgcn_s_barrier()
; #define PG8_SCHED __builtin_amdgcn_sched_barrier(0)
; template <class Epi, class Sched, bool ALIGN_EPI = false, bool SP2 = false>
; __device__ __forceinline__ void gemm_phase(PG8_LAS unsigned char* lds, const Gemm g, const Sched& S, const Epi& E) {
;     ...
;         const bool has_next = S.next(ui + 1, nxt);
;         const char* nA = has_next ? (const char*)g.A + (size_t)nxt.pm * tstep : cA; const char* nB = has_next ? (const char*)g.Bt + (size_t)nxt.pn * tstep : cB;
;         for (int t = 0; t < nt; t += 2) {
;             const bool last = (t == nt - 2);
;             const char* a1 = cA + (size_t)(t + 1) * kstep;
;             const char* a2 = last ? nA : cA + (size_t)(t + 2) * kstep; const char* b2 = last ? nB : cB + (size_t)(t + 2) * kstep;
;             const char* a3 = a2 + kstep; const char* b3 = b2 + kstep;
;             if (last && has_next) S.a_ready(nxt);
;             if constexpr (SP2) {
;             PG8_LDB(B0, 0, 0); PG8_LDB(B1, 0, 1); PG8_SCHED; PG8_LDA(At, 0, 0); PG8_STAGE(PG8_SA(1, 1), a1 + hstep, voffA);
;             PG8_WAIT_V(8); PG8_WAIT_L(0); PG8_BAR; PG8_MMA(0, 0, At, B0); PG8_MMA(0, 1, At, B1); PG8_BAR; PG8_SCHED;
;             PG8_LDA(At, 0, 1); PG8_STAGE(PG8_SB(0, 0), b2, voffB); PG8_STAGE(PG8_SB(0, 1), b2 + hstep, voffB); PG8_STAGE(PG8_SA(0, 0), a2, voffA);
.LBB0_204:
	s_ashr_i32 s21, s20, 31
	s_lshl_b64 s[24:25], s[20:21], 20
	v_readlane_b32 s26, v236, 50
	v_readlane_b32 s27, v236, 51
	s_add_u32 s24, s26, s24
	s_addc_u32 s25, s27, s25
	s_and_b64 s[26:27], s[8:9], exec
	s_cselect_b32 s1, s25, s5
	s_cselect_b32 s3, s24, s4
	s_ashr_i32 s23, s22, 31
	s_lshl_b64 s[26:27], s[22:23], 20
	s_add_u32 s26, s10, s26
	s_addc_u32 s27, s11, s27
	s_and_b64 s[28:29], s[8:9], exec
	s_cselect_b32 s21, s27, s7
	s_cselect_b32 s23, s26, s6
	s_add_u32 s4, s4, 0x80080
	s_addc_u32 s5, s5, 0
	s_add_u32 s33, s6, 0x100
	s_addc_u32 s50, s7, 0
	s_mov_b32 s51, -2
	s_waitcnt vmcnt(0)
	ds_read_b128 v[128:131], v190
	ds_read_b128 v[132:135], v190 offset:1024
	ds_read_b128 v[136:139], v190 offset:2048
	ds_read_b128 v[140:143], v190 offset:3072
	ds_read_b128 v[144:147], v191
	ds_read_b128 v[148:151], v191 offset:1024
	ds_read_b128 v[152:155], v191 offset:2048
	ds_read_b128 v[156:159], v191 offset:3072
	s_add_u32 s6, s4, 0xfff80080
	s_addc_u32 s7, s5, -1
	s_cmp_eq_u32 s51, 28
	s_cselect_b32 s29, s1, s7
	s_cselect_b32 s28, s3, s6
	s_cselect_b32 s7, s21, s50
	s_cselect_b32 s6, s23, s33
	v_lshl_add_u64 v[184:185], s[4:5], 0, v[172:173]
	s_add_i32 m0, s31, 0xc000
	ds_read_b128 v[180:183], v192
	ds_read_b128 v[194:197], v192 offset:1024
	ds_read_b128 v[198:201], v192 offset:2048
	ds_read_b128 v[202:205], v192 offset:3072
	ds_read_b128 v[206:209], v192 offset:4096
	ds_read_b128 v[210:213], v192 offset:5120
	ds_read_b128 v[214:217], v192 offset:6144
	ds_read_b128 v[218:221], v192 offset:7168
	global_load_lds_dwordx4 v[184:185], off
	v_lshl_add_u64 v[184:185], s[4:5], 0, v[174:175]
	s_add_i32 m0, s31, 0xe000
	s_nop 0
	global_load_lds_dwordx4 v[184:185], off
	s_waitcnt vmcnt(8)
	s_waitcnt lgkmcnt(0)
	s_barrier
	s_setprio 1
	s_waitcnt lgkmcnt(0)
	v_mfma_f32_16x16x32_bf16 v[124:127], v[128:131], v[180:183], 0
	v_mfma_f32_16x16x32_bf16 v[120:123], v[136:139], v[180:183], 0
	v_mfma_f32_16x16x32_bf16 v[108:111], v[128:131], v[198:201], 0
	v_mfma_f32_16x16x32_bf16 v[104:107], v[136:139], v[198:201], 0
	v_mfma_f32_16x16x32_bf16 v[92:95], v[128:131], v[206:209], 0
	v_mfma_f32_16x16x32_bf16 v[88:91], v[136:139], v[206:209], 0
	v_mfma_f32_16x16x32_bf16 v[76:79], v[128:131], v[214:217], 0
	v_mfma_f32_16x16x32_bf16 v[72:75], v[136:139], v[214:217], 0
	v_mfma_f32_16x16x32_bf16 v[124:127], v[132:135], v[194:197], v[124:127]
	v_mfma_f32_16x16x32_bf16 v[120:123], v[140:143], v[194:197], v[120:123]
	v_mfma_f32_16x16x32_bf16 v[108:111], v[132:135], v[202:205], v[108:111]
	v_mfma_f32_16x16x32_bf16 v[104:107], v[140:143], v[202:205], v[104:107]
	v_mfma_f32_16x16x32_bf16 v[92:95], v[132:135], v[210:213], v[92:95]
	v_mfma_f32_16x16x32_bf16 v[88:91], v[140:143], v[210:213], v[88:91]
	v_mfma_f32_16x16x32_bf16 v[76:79], v[132:135], v[218:221], v[76:79]
	v_mfma_f32_16x16x32_bf16 v[72:75], v[140:143], v[218:221], v[72:75]
	s_setprio 0
	s_setprio 1
	v_mfma_f32_16x16x32_bf16 v[116:119], v[144:147], v[180:183], 0
	v_mfma_f32_16x16x32_bf16 v[112:115], v[152:155], v[180:183], 0
	v_mfma_f32_16x16x32_bf16 v[100:103], v[144:147], v[198:201], 0
	v_mfma_f32_16x16x32_bf16 v[96:99], v[152:155], v[198:201], 0
	v_mfma_f32_16x16x32_bf16 v[84:87], v[144:147], v[206:209], 0
	v_mfma_f32_16x16x32_bf16 v[80:83], v[152:155], v[206:209], 0
	v_mfma_f32_16x16x32_bf16 v[68:71], v[144:147], v[214:217], 0
	v_mfma_f32_16x16x32_bf16 v[64:67], v[152:155], v[214:217], 0
	v_mfma_f32_16x16x32_bf16 v[116:119], v[148:151], v[194:197], v[116:119]
	v_mfma_f32_16x16x32_bf16 v[112:115], v[156:159], v[194:197], v[112:115]
	v_mfma_f32_16x16x32_bf16 v[100:103], v[148:151], v[202:205], v[100:103]
	v_mfma_f32_16x16x32_bf16 v[96:99], v[156:159], v[202:205], v[96:99]
	v_mfma_f32_16x16x32_bf16 v[84:87], v[148:151], v[210:213], v[84:87]
	v_mfma_f32_16x16x32_bf16 v[80:83], v[156:159], v[210:213], v[80:83]
	v_mfma_f32_16x16x32_bf16 v[68:71], v[148:151], v[218:221], v[68:71]
	v_mfma_f32_16x16x32_bf16 v[64:67], v[156:159], v[218:221], v[64:67]
	s_setprio 0
	s_barrier
	s_add_i32 s52, s43, s30
	v_lshl_add_u64 v[184:185], s[6:7], 0, v[164:165]
	s_mov_b32 m0, s52
	ds_read_b128 v[180:183], v192 offset:16384
	ds_read_b128 v[194:197], v192 offset:17408
	ds_read_b128 v[198:201], v192 offset:18432
	ds_read_b128 v[202:205], v192 offset:19456
	ds_read_b128 v[206:209], v192 offset:20480
	ds_read_b128 v[210:213], v192 offset:21504
	ds_read_b128 v[214:217], v192 offset:22528
	ds_read_b128 v[218:221], v192 offset:23552
	global_load_lds_dwordx4 v[184:185], off
	s_add_i32 m0, s52, 0x2000
	s_add_u32 s52, s6, 0x80000
	v_lshl_add_u64 v[222:223], s[6:7], 0, v[168:169]
	s_addc_u32 s53, s7, 0
	s_add_i32 s54, s44, s30
	global_load_lds_dwordx4 v[222:223], off
	v_lshl_add_u64 v[224:225], s[52:53], 0, v[164:165]
	s_mov_b32 m0, s54
	v_lshl_add_u64 v[226:227], s[28:29], 0, v[166:167]
	global_load_lds_dwordx4 v[224:225], off
	v_lshl_add_u64 v[224:225], s[52:53], 0, v[168:169]
	s_add_i32 m0, s54, 0x2000
	s_nop 0
	global_load_lds_dwordx4 v[224:225], off
	v_lshl_add_u64 v[224:225], s[28:29], 0, v[162:163]
	s_mov_b32 m0, s31
	s_nop 0
	global_load_lds_dwordx4 v[224:225], off
	s_mov_b32 m0, s34
	s_nop 0
	global_load_lds_dwordx4 v[226:227], off
	s_waitcnt vmcnt(8)
	s_waitcnt lgkmcnt(0)
	s_barrier
; #define PG8_STAGE(bufoff, gbase, voff) do { _Pragma("unroll") for (int _i = 0; _i < 2; ++_i) \
;         __builtin_amdgcn_global_load_lds((const unsigned*)((const char*)(gbase) + (voff)[_i]), (PG8_LAS unsigned*)(lds + (bufoff) + ldsw + _i * 8192), 16, 0, 0); } while (0)
; #define PG8_LDA(dst, b, h) do { _Pragma("unroll") for (int m = 0; m < 4; ++m) _Pragma("unroll") for (int k = 0; k < 2; ++k) dst[m][k] = *(const PG8_LAS bf16x8*)(lds + PG8_SA(b, h) + aoff + m * 2048 + k * 1024); } while (0)
; #define PG8_LDB(dst, b, h) do { _Pragma("unroll") for (int n = 0; n < 2; ++n) _Pragma("unroll") for (int k = 0; k < 2; ++k) dst[n][k] = *(const PG8_LAS bf16x8*)(lds + PG8_SB(b, h) + boff + n * 2048 + k * 1024); } while (0)
; #define PG8_MMA(ai, bj, At, Bt) do { __builtin_amdgcn_s_setprio(1); _Pragma("unroll") for (int m = 0; m < 4; ++m) _Pragma("unroll") for (int n = 0; n < 2; ++n) _Pragma("unroll") for (int k = 0; k < 2; ++k) \
;         acc[ai][bj][m][n] = __builtin_amdgcn_mfma_f32_16x16x32_bf16(Bt[n][k], At[m][k], acc[ai][bj][m][n], 0, 0, 0); __builtin_amdgcn_s_setprio(0); } while (0)
; #define PG8_WAIT_V(n) asm volatile("s_waitcnt vmcnt(" #n ")" ::: "memory")
; #define PG8_WAIT_L(n) asm volatile("s_waitcnt lgkmcnt(" #n ")" ::: "memory")
; #define PG8_BAR __builtin_amdgcn_s_barrier()
; #define PG8_SCHED __builtin_amdgcn_sched_barrier(0)
; template <class Epi, class Sched, bool ALIGN_EPI = false, bool SP2 = false>
; __device__ __forceinline__ void gemm_phase(PG8_LAS unsigned char* lds, const Gemm g, const Sched& S, const Epi& E) {
;     ...
;             PG8_WAIT_V(8); PG8_WAIT_L(0); PG8_BAR; PG8_MMA(1, 0, At, B0); PG8_MMA(1, 1, At, B1); PG8_BAR; PG8_SCHED;
;             PG8_LDB(B0, 1, 0); PG8_LDB(B1, 1, 1); PG8_SCHED; PG8_LDA(At, 1, 0); PG8_STAGE(PG8_SA(0, 1), a2 + hstep, voffA);
;             PG8_WAIT_V(8); PG8_WAIT_L(0); PG8_BAR; PG8_MMA(0, 0, At, B0); PG8_MMA(0, 1, At, B1); PG8_BAR; PG8_SCHED;
	s_setprio 1
	s_waitcnt lgkmcnt(0)
	v_mfma_f32_16x16x32_bf16 v[60:63], v[128:131], v[180:183], 0
	v_mfma_f32_16x16x32_bf16 v[56:59], v[136:139], v[180:183], 0
	v_mfma_f32_16x16x32_bf16 v[44:47], v[128:131], v[198:201], 0
	v_mfma_f32_16x16x32_bf16 v[40:43], v[136:139], v[198:201], 0
	v_mfma_f32_16x16x32_bf16 v[28:31], v[128:131], v[206:209], 0
	v_mfma_f32_16x16x32_bf16 v[24:27], v[136:139], v[206:209], 0
	v_mfma_f32_16x16x32_bf16 v[12:15], v[128:131], v[214:217], 0
	v_mfma_f32_16x16x32_bf16 v[8:11], v[136:139], v[214:217], 0
	v_mfma_f32_16x16x32_bf16 v[60:63], v[132:135], v[194:197], v[60:63]
	v_mfma_f32_16x16x32_bf16 v[56:59], v[140:143], v[194:197], v[56:59]
	v_mfma_f32_16x16x32_bf16 v[44:47], v[132:135], v[202:205], v[44:47]
	v_mfma_f32_16x16x32_bf16 v[40:43], v[140:143], v[202:205], v[40:43]
	v_mfma_f32_16x16x32_bf16 v[28:31], v[132:135], v[210:213], v[28:31]
	v_mfma_f32_16x16x32_bf16 v[24:27], v[140:143], v[210:213], v[24:27]
	v_mfma_f32_16x16x32_bf16 v[12:15], v[132:135], v[218:221], v[12:15]
	v_mfma_f32_16x16x32_bf16 v[8:11], v[140:143], v[218:221], v[8:11]
	s_setprio 0
	s_setprio 1
	v_mfma_f32_16x16x32_bf16 v[52:55], v[144:147], v[180:183], 0
	v_mfma_f32_16x16x32_bf16 v[48:51], v[152:155], v[180:183], 0
	v_mfma_f32_16x16x32_bf16 v[36:39], v[144:147], v[198:201], 0
	v_mfma_f32_16x16x32_bf16 v[32:35], v[152:155], v[198:201], 0
	v_mfma_f32_16x16x32_bf16 v[20:23], v[144:147], v[206:209], 0
	v_mfma_f32_16x16x32_bf16 v[16:19], v[152:155], v[206:209], 0
	v_mfma_f32_16x16x32_bf16 v[4:7], v[144:147], v[214:217], 0
	v_mfma_f32_16x16x32_bf16 v[0:3], v[152:155], v[214:217], 0
	v_mfma_f32_16x16x32_bf16 v[52:55], v[148:151], v[194:197], v[52:55]
	v_mfma_f32_16x16x32_bf16 v[48:51], v[156:159], v[194:197], v[48:51]
	v_mfma_f32_16x16x32_bf16 v[36:39], v[148:151], v[202:205], v[36:39]
	v_mfma_f32_16x16x32_bf16 v[32:35], v[156:159], v[202:205], v[32:35]
	v_mfma_f32_16x16x32_bf16 v[20:23], v[148:151], v[210:213], v[20:23]
	v_mfma_f32_16x16x32_bf16 v[16:19], v[156:159], v[210:213], v[16:19]
	v_mfma_f32_16x16x32_bf16 v[4:7], v[148:151], v[218:221], v[4:7]
	v_mfma_f32_16x16x32_bf16 v[0:3], v[156:159], v[218:221], v[0:3]
	s_setprio 0
	s_barrier
	s_add_i32 s52, 0, 0x18000
	s_add_i32 s53, 0, 0x1c000
	v_add_u32_e32 v140, s52, v188
	v_add_u32_e32 v156, s53, v188
	ds_read_b128 v[128:131], v140
	ds_read_b128 v[132:135], v140 offset:1024
	ds_read_b128 v[136:139], v140 offset:2048
	ds_read_b128 v[140:143], v140 offset:3072
	ds_read_b128 v[144:147], v156
	ds_read_b128 v[148:151], v156 offset:1024
	ds_read_b128 v[152:155], v156 offset:2048
	ds_read_b128 v[156:159], v156 offset:3072
	s_add_u32 s28, s28, 0x80000
	s_addc_u32 s29, s29, 0
	s_mov_b32 m0, s35
	v_lshl_add_u64 v[228:229], s[28:29], 0, v[162:163]
	ds_read_b128 v[180:183], v192 offset:32768
	ds_read_b128 v[194:197], v192 offset:33792
	ds_read_b128 v[198:201], v192 offset:34816
	ds_read_b128 v[202:205], v192 offset:35840
	ds_read_b128 v[206:209], v192 offset:36864
	ds_read_b128 v[210:213], v192 offset:37888
	ds_read_b128 v[214:217], v192 offset:38912
	ds_read_b128 v[218:221], v192 offset:39936
	global_load_lds_dwordx4 v[228:229], off
	v_lshl_add_u64 v[228:229], s[28:29], 0, v[166:167]
	s_mov_b32 m0, s36
	s_nop 0
	global_load_lds_dwordx4 v[228:229], off
	s_waitcnt vmcnt(8)
	s_waitcnt lgkmcnt(0)
	s_barrier
	s_setprio 1
	s_waitcnt lgkmcnt(0)
	v_mfma_f32_16x16x32_bf16 v[124:127], v[128:131], v[180:183], v[124:127]
	v_mfma_f32_16x16x32_bf16 v[120:123], v[136:139], v[180:183], v[120:123]
	v_mfma_f32_16x16x32_bf16 v[108:111], v[128:131], v[198:201], v[108:111]
	v_mfma_f32_16x16x32_bf16 v[104:107], v[136:139], v[198:201], v[104:107]
	v_mfma_f32_16x16x32_bf16 v[92:95], v[128:131], v[206:209], v[92:95]
	v_mfma_f32_16x16x32_bf16 v[88:91], v[136:139], v[206:209], v[88:91]
	v_mfma_f32_16x16x32_bf16 v[76:79], v[128:131], v[214:217], v[76:79]
	v_mfma_f32_16x16x32_bf16 v[72:75], v[136:139], v[214:217], v[72:75]
	v_mfma_f32_16x16x32_bf16 v[124:127], v[132:135], v[194:197], v[124:127]
	v_mfma_f32_16x16x32_bf16 v[120:123], v[140:143], v[194:197], v[120:123]
	v_mfma_f32_16x16x32_bf16 v[108:111], v[132:135], v[202:205], v[108:111]
	v_mfma_f32_16x16x32_bf16 v[104:107], v[140:143], v[202:205], v[104:107]
	v_mfma_f32_16x16x32_bf16 v[92:95], v[132:135], v[210:213], v[92:95]
	v_mfma_f32_16x16x32_bf16 v[88:91], v[140:143], v[210:213], v[88:91]
	v_mfma_f32_16x16x32_bf16 v[76:79], v[132:135], v[218:221], v[76:79]
	v_mfma_f32_16x16x32_bf16 v[72:75], v[140:143], v[218:221], v[72:75]
	s_setprio 0
	s_setprio 1
	v_mfma_f32_16x16x32_bf16 v[116:119], v[144:147], v[180:183], v[116:119]
	v_mfma_f32_16x16x32_bf16 v[112:115], v[152:155], v[180:183], v[112:115]
	v_mfma_f32_16x16x32_bf16 v[100:103], v[144:147], v[198:201], v[100:103]
	v_mfma_f32_16x16x32_bf16 v[96:99], v[152:155], v[198:201], v[96:99]
	v_mfma_f32_16x16x32_bf16 v[84:87], v[144:147], v[206:209], v[84:87]
	v_mfma_f32_16x16x32_bf16 v[80:83], v[152:155], v[206:209], v[80:83]
	v_mfma_f32_16x16x32_bf16 v[68:71], v[144:147], v[214:217], v[68:71]
	v_mfma_f32_16x16x32_bf16 v[64:67], v[152:155], v[214:217], v[64:67]
	v_mfma_f32_16x16x32_bf16 v[116:119], v[148:151], v[194:197], v[116:119]
	v_mfma_f32_16x16x32_bf16 v[112:115], v[156:159], v[194:197], v[112:115]
	v_mfma_f32_16x16x32_bf16 v[100:103], v[148:151], v[202:205], v[100:103]
	v_mfma_f32_16x16x32_bf16 v[96:99], v[156:159], v[202:205], v[96:99]
	v_mfma_f32_16x16x32_bf16 v[84:87], v[148:151], v[210:213], v[84:87]
	v_mfma_f32_16x16x32_bf16 v[80:83], v[156:159], v[210:213], v[80:83]
	v_mfma_f32_16x16x32_bf16 v[68:71], v[148:151], v[218:221], v[68:71]
	v_mfma_f32_16x16x32_bf16 v[64:67], v[156:159], v[218:221], v[64:67]
	s_setprio 0
	s_barrier
; #define PG8_STAGE(bufoff, gbase, voff) do { _Pragma("unroll") for (int _i = 0; _i < 2; ++_i) \
;         __builtin_amdgcn_global_load_lds((const unsigned*)((const char*)(gbase) + (voff)[_i]), (PG8_LAS unsigned*)(lds + (bufoff) + ldsw + _i * 8192), 16, 0, 0); } while (0)
; #define PG8_LDA(dst, b, h) do { _Pragma("unroll") for (int m = 0; m < 4; ++m) _Pragma("unroll") for (int k = 0; k < 2; ++k) dst[m][k] = *(const PG8_LAS bf16x8*)(lds + PG8_SA(b, h) + aoff + m * 2048 + k * 1024); } while (0)
; #define PG8_MMA(ai, bj, At, Bt) do { __builtin_amdgcn_s_setprio(1); _Pragma("unroll") for (int m = 0; m < 4; ++m) _Pragma("unroll") for (int n = 0; n < 2; ++n) _Pragma("unroll") for (int k = 0; k < 2; ++k) \
;         acc[ai][bj][m][n] = __builtin_amdgcn_mfma_f32_16x16x32_bf16(Bt[n][k], At[m][k], acc[ai][bj][m][n], 0, 0, 0); __builtin_amdgcn_s_setprio(0); } while (0)
; #define PG8_WAIT_V(n) asm volatile("s_waitcnt vmcnt(" #n ")" ::: "memory")
; #define PG8_WAIT_L(n) asm volatile("s_waitcnt lgkmcnt(" #n ")" ::: "memory")
; #define PG8_BAR __builtin_amdgcn_s_barrier()
; #define PG8_SCHED __builtin_amdgcn_sched_barrier(0)
; template <class Epi, class Sched, bool ALIGN_EPI = false, bool SP2 = false>
; __device__ __forceinline__ void gemm_phase(PG8_LAS unsigned char* lds, const Gemm g, const Sched& S, const Epi& E) {
;     ...
;             PG8_LDA(At, 1, 1); PG8_STAGE(PG8_SB(1, 0), b3, voffB); PG8_STAGE(PG8_SB(1, 1), b3 + hstep, voffB); PG8_STAGE(PG8_SA(1, 0), a3, voffA);
;             PG8_WAIT_V(8); PG8_WAIT_L(0); PG8_BAR; PG8_MMA(1, 0, At, B0); PG8_MMA(1, 1, At, B1); PG8_BAR; PG8_SCHED;
	s_add_i32 s28, s52, s30
	v_lshl_add_u64 v[184:185], v[184:185], 0, s[16:17]
	s_mov_b32 m0, s28
	ds_read_b128 v[180:183], v192 offset:49152
	ds_read_b128 v[194:197], v192 offset:50176
	ds_read_b128 v[198:201], v192 offset:51200
	ds_read_b128 v[202:205], v192 offset:52224
	ds_read_b128 v[206:209], v192 offset:53248
	ds_read_b128 v[210:213], v192 offset:54272
	ds_read_b128 v[214:217], v192 offset:55296
	ds_read_b128 v[218:221], v192 offset:56320
	global_load_lds_dwordx4 v[184:185], off
	s_add_i32 m0, s28, 0x2000
	s_add_u32 s6, s6, 0x80080
	v_lshl_add_u64 v[184:185], v[222:223], 0, s[16:17]
	s_addc_u32 s7, s7, 0
	s_add_i32 s28, s53, s30
	global_load_lds_dwordx4 v[184:185], off
	v_lshl_add_u64 v[184:185], s[6:7], 0, v[164:165]
	s_mov_b32 m0, s28
	s_nop 0
	global_load_lds_dwordx4 v[184:185], off
	v_lshl_add_u64 v[184:185], s[6:7], 0, v[168:169]
	s_add_i32 m0, s28, 0x2000
	s_nop 0
	global_load_lds_dwordx4 v[184:185], off
	v_lshl_add_u64 v[184:185], v[224:225], 0, s[16:17]
	s_mov_b32 m0, s38
	s_nop 0
	global_load_lds_dwordx4 v[184:185], off
	v_lshl_add_u64 v[184:185], v[226:227], 0, s[16:17]
	s_mov_b32 m0, s39
	s_nop 0
	global_load_lds_dwordx4 v[184:185], off
	s_waitcnt vmcnt(8)
	s_waitcnt lgkmcnt(0)
	s_barrier
	s_setprio 1
	s_waitcnt lgkmcnt(0)
	v_mfma_f32_16x16x32_bf16 v[60:63], v[128:131], v[180:183], v[60:63]
	v_mfma_f32_16x16x32_bf16 v[56:59], v[136:139], v[180:183], v[56:59]
	v_mfma_f32_16x16x32_bf16 v[44:47], v[128:131], v[198:201], v[44:47]
	v_mfma_f32_16x16x32_bf16 v[40:43], v[136:139], v[198:201], v[40:43]
	v_mfma_f32_16x16x32_bf16 v[28:31], v[128:131], v[206:209], v[28:31]
	v_mfma_f32_16x16x32_bf16 v[24:27], v[136:139], v[206:209], v[24:27]
	v_mfma_f32_16x16x32_bf16 v[12:15], v[128:131], v[214:217], v[12:15]
	v_mfma_f32_16x16x32_bf16 v[8:11], v[136:139], v[214:217], v[8:11]
	v_mfma_f32_16x16x32_bf16 v[60:63], v[132:135], v[194:197], v[60:63]
	v_mfma_f32_16x16x32_bf16 v[56:59], v[140:143], v[194:197], v[56:59]
	v_mfma_f32_16x16x32_bf16 v[44:47], v[132:135], v[202:205], v[44:47]
	v_mfma_f32_16x16x32_bf16 v[40:43], v[140:143], v[202:205], v[40:43]
	v_mfma_f32_16x16x32_bf16 v[28:31], v[132:135], v[210:213], v[28:31]
	v_mfma_f32_16x16x32_bf16 v[24:27], v[140:143], v[210:213], v[24:27]
	v_mfma_f32_16x16x32_bf16 v[12:15], v[132:135], v[218:221], v[12:15]
	v_mfma_f32_16x16x32_bf16 v[8:11], v[140:143], v[218:221], v[8:11]
	s_setprio 0
	s_setprio 1
	v_mfma_f32_16x16x32_bf16 v[52:55], v[144:147], v[180:183], v[52:55]
	v_mfma_f32_16x16x32_bf16 v[48:51], v[152:155], v[180:183], v[48:51]
	v_mfma_f32_16x16x32_bf16 v[36:39], v[144:147], v[198:201], v[36:39]
	v_mfma_f32_16x16x32_bf16 v[32:35], v[152:155], v[198:201], v[32:35]
	v_mfma_f32_16x16x32_bf16 v[20:23], v[144:147], v[206:209], v[20:23]
	v_mfma_f32_16x16x32_bf16 v[16:19], v[152:155], v[206:209], v[16:19]
	v_mfma_f32_16x16x32_bf16 v[4:7], v[144:147], v[214:217], v[4:7]
	v_mfma_f32_16x16x32_bf16 v[0:3], v[152:155], v[214:217], v[0:3]
	v_mfma_f32_16x16x32_bf16 v[52:55], v[148:151], v[194:197], v[52:55]
	v_mfma_f32_16x16x32_bf16 v[48:51], v[156:159], v[194:197], v[48:51]
	v_mfma_f32_16x16x32_bf16 v[36:39], v[148:151], v[202:205], v[36:39]
	v_mfma_f32_16x16x32_bf16 v[32:35], v[156:159], v[202:205], v[32:35]
	v_mfma_f32_16x16x32_bf16 v[20:23], v[148:151], v[210:213], v[20:23]
	v_mfma_f32_16x16x32_bf16 v[16:19], v[156:159], v[210:213], v[16:19]
	v_mfma_f32_16x16x32_bf16 v[4:7], v[148:151], v[218:221], v[4:7]
	v_mfma_f32_16x16x32_bf16 v[0:3], v[156:159], v[218:221], v[0:3]
	s_setprio 0
	s_barrier
	s_add_i32 s51, s51, 2
	s_add_u32 s4, s4, 0x100
	s_addc_u32 s5, s5, 0
	s_add_u32 s33, s33, 0x100
	s_addc_u32 s50, s50, 0
	s_cmp_gt_u32 s51, 29

;     __device__ __forceinline__ bool next(int i, Unit& u) const { if (!base.next(i >> 1, u)) return false; if (i & 1) { u.pm += 64; u.pn += 8; } return true; }
; #define PG8_STAGE(bufoff, gbase, voff) do { _Pragma("unroll") for (int _i = 0; _i < 2; ++_i) \
;         __builtin_amdgcn_global_load_lds((const unsigned*)((const char*)(gbase) + (voff)[_i]), (PG8_LAS unsigned*)(lds + (bufoff) + ldsw + _i * 8192), 16, 0, 0); } while (0)
; #define PG8_LDA(dst, b, h) do { _Pragma("unroll") for (int m = 0; m < 4; ++m) _Pragma("unroll") for (int k = 0; k < 2; ++k) dst[m][k] = *(const PG8_LAS bf16x8*)(lds + PG8_SA(b, h) + aoff + m * 2048 + k * 1024); } while (0)
; #define PG8_LDB(dst, b, h) do { _Pragma("unroll") for (int n = 0; n < 2; ++n) _Pragma("unroll") for (int k = 0; k < 2; ++k) dst[n][k] = *(const PG8_LAS bf16x8*)(lds + PG8_SB(b, h) + boff + n * 2048 + k * 1024); } while (0)
; #define PG8_WAIT_V(n) asm volatile("s_waitcnt vmcnt(" #n ")" ::: "memory")
; #define PG8_WAIT_L(n) asm volatile("s_waitcnt lgkmcnt(" #n ")" ::: "memory")
; #define PG8_BAR __builtin_amdgcn_s_barrier()
; #define PG8_SCHED __builtin_amdgcn_sched_barrier(0)
; template <class Epi, class Sched, bool ALIGN_EPI = false, bool SP2 = false>
; __device__ __forceinline__ void gemm_phase(PG8_LAS unsigned char* lds, const Gemm g, const Sched& S, const Epi& E) {
;     ...
;         const bool has_next = S.next(ui + 1, nxt);
;         const char* nA = has_next ? (const char*)g.A + (size_t)nxt.pm * tstep : cA; const char* nB = has_next ? (const char*)g.Bt + (size_t)nxt.pn * tstep : cB;
;         for (int t = 0; t < nt; t += 2) {
;             const bool last = (t == nt - 2);
;             const char* a1 = cA + (size_t)(t + 1) * kstep;
;             const char* a2 = last ? nA : cA + (size_t)(t + 2) * kstep; const char* b2 = last ? nB : cB + (size_t)(t + 2) * kstep;
;             const char* a3 = a2 + kstep; const char* b3 = b2 + kstep;
;             if (last && has_next) S.a_ready(nxt);
;             if constexpr (SP2) {
;             PG8_LDB(B0, 0, 0); PG8_LDB(B1, 0, 1); PG8_SCHED; PG8_LDA(At, 0, 0); PG8_STAGE(PG8_SA(1, 1), a1 + hstep, voffA);
;             PG8_WAIT_V(8); PG8_WAIT_L(0); PG8_BAR; PG8_MMA(0, 0, At, B0); PG8_MMA(0, 1, At, B1); PG8_BAR; PG8_SCHED;
;             PG8_LDA(At, 0, 1); PG8_STAGE(PG8_SB(0, 0), b2, voffB); PG8_STAGE(PG8_SB(0, 1), b2 + hstep, voffB); PG8_STAGE(PG8_SA(0, 0), a2, voffA);
.LBB0_571:
	s_bitcmp0_b32 s7, 0
	s_cselect_b64 s[16:17], -1, 0
	s_and_b64 s[16:17], s[16:17], s[4:5]
	s_add_i32 s7, s14, 64
	s_add_i32 s13, s12, 8
	s_and_b64 s[16:17], s[16:17], exec
	s_cselect_b32 s14, s7, s14
	s_cselect_b32 s12, s13, s12
	s_ashr_i32 s15, s14, 31
	s_lshl_b64 s[16:17], s[14:15], 19
	s_add_u32 s16, s29, s16
	s_addc_u32 s17, s30, s17
	s_and_b64 s[18:19], s[4:5], exec
	s_cselect_b32 s7, s17, s23
	s_cselect_b32 s15, s16, s22
	s_ashr_i32 s13, s12, 31
	s_lshl_b64 s[18:19], s[12:13], 19
	v_readlane_b32 s26, v236, 41
	v_readlane_b32 s27, v236, 42
	s_add_u32 s18, s26, s18
	s_addc_u32 s19, s27, s19
	s_and_b64 s[26:27], s[4:5], exec
	s_cselect_b32 s13, s19, s25
	s_cselect_b32 s21, s18, s24
	s_add_u32 s22, s22, 0x40080
	s_addc_u32 s23, s23, 0
	s_add_u32 s44, s24, 0x100
	s_addc_u32 s45, s25, 0
	s_mov_b32 s46, -2
	ds_read_b128 v[146:149], v159
	ds_read_b128 v[150:153], v159 offset:1024
	ds_read_b128 v[164:167], v159 offset:2048
	ds_read_b128 v[168:171], v159 offset:3072
	ds_read_b128 v[172:175], v161
	ds_read_b128 v[176:179], v161 offset:1024
	ds_read_b128 v[180:183], v161 offset:2048
	ds_read_b128 v[188:191], v161 offset:3072
	s_add_u32 s24, s22, 0xfffc0080
	s_addc_u32 s25, s23, -1
	s_cmp_eq_u32 s46, 12
	s_cselect_b32 s27, s7, s25
	s_cselect_b32 s26, s15, s24
	s_cselect_b32 s25, s13, s45
	s_cselect_b32 s24, s21, s44
	v_lshl_add_u64 v[154:155], s[22:23], 0, v[138:139]
	s_add_i32 m0, s31, 0xc000
	ds_read_b128 v[192:195], v162
	ds_read_b128 v[196:199], v162 offset:1024
	ds_read_b128 v[200:203], v162 offset:2048
	ds_read_b128 v[204:207], v162 offset:3072
	ds_read_b128 v[208:211], v162 offset:4096
	ds_read_b128 v[212:215], v162 offset:5120
	ds_read_b128 v[216:219], v162 offset:6144
	ds_read_b128 v[220:223], v162 offset:7168
	global_load_lds_dwordx4 v[154:155], off
	v_lshl_add_u64 v[154:155], s[22:23], 0, v[140:141]
	s_add_i32 m0, s31, 0xe000
	s_nop 0
	global_load_lds_dwordx4 v[154:155], off
	s_waitcnt vmcnt(8)
	s_waitcnt lgkmcnt(0)
	s_barrier
	s_setprio 1
	s_waitcnt lgkmcnt(0)
	v_mfma_f32_16x16x32_bf16 v[124:127], v[146:149], v[192:195], 0
	v_mfma_f32_16x16x32_bf16 v[120:123], v[164:167], v[192:195], 0
	v_mfma_f32_16x16x32_bf16 v[108:111], v[146:149], v[200:203], 0
	v_mfma_f32_16x16x32_bf16 v[104:107], v[164:167], v[200:203], 0
	v_mfma_f32_16x16x32_bf16 v[92:95], v[146:149], v[208:211], 0
	v_mfma_f32_16x16x32_bf16 v[88:91], v[164:167], v[208:211], 0
	v_mfma_f32_16x16x32_bf16 v[76:79], v[146:149], v[216:219], 0
	v_mfma_f32_16x16x32_bf16 v[72:75], v[164:167], v[216:219], 0
	v_mfma_f32_16x16x32_bf16 v[124:127], v[150:153], v[196:199], v[124:127]
	v_mfma_f32_16x16x32_bf16 v[120:123], v[168:171], v[196:199], v[120:123]
	v_mfma_f32_16x16x32_bf16 v[108:111], v[150:153], v[204:207], v[108:111]
	v_mfma_f32_16x16x32_bf16 v[104:107], v[168:171], v[204:207], v[104:107]
	v_mfma_f32_16x16x32_bf16 v[92:95], v[150:153], v[212:215], v[92:95]
	v_mfma_f32_16x16x32_bf16 v[88:91], v[168:171], v[212:215], v[88:91]
	v_mfma_f32_16x16x32_bf16 v[76:79], v[150:153], v[220:223], v[76:79]
	v_mfma_f32_16x16x32_bf16 v[72:75], v[168:171], v[220:223], v[72:75]
	s_setprio 0
	s_setprio 1
	v_mfma_f32_16x16x32_bf16 v[116:119], v[172:175], v[192:195], 0
	v_mfma_f32_16x16x32_bf16 v[112:115], v[180:183], v[192:195], 0
	v_mfma_f32_16x16x32_bf16 v[100:103], v[172:175], v[200:203], 0
	v_mfma_f32_16x16x32_bf16 v[96:99], v[180:183], v[200:203], 0
	v_mfma_f32_16x16x32_bf16 v[84:87], v[172:175], v[208:211], 0
	v_mfma_f32_16x16x32_bf16 v[80:83], v[180:183], v[208:211], 0
	v_mfma_f32_16x16x32_bf16 v[68:71], v[172:175], v[216:219], 0
	v_mfma_f32_16x16x32_bf16 v[64:67], v[180:183], v[216:219], 0
	v_mfma_f32_16x16x32_bf16 v[116:119], v[176:179], v[196:199], v[116:119]
	v_mfma_f32_16x16x32_bf16 v[112:115], v[188:191], v[196:199], v[112:115]
	v_mfma_f32_16x16x32_bf16 v[100:103], v[176:179], v[204:207], v[100:103]
	v_mfma_f32_16x16x32_bf16 v[96:99], v[188:191], v[204:207], v[96:99]
	v_mfma_f32_16x16x32_bf16 v[84:87], v[176:179], v[212:215], v[84:87]
	v_mfma_f32_16x16x32_bf16 v[80:83], v[188:191], v[212:215], v[80:83]
	v_mfma_f32_16x16x32_bf16 v[68:71], v[176:179], v[220:223], v[68:71]
	v_mfma_f32_16x16x32_bf16 v[64:67], v[188:191], v[220:223], v[64:67]
	s_setprio 0
	s_barrier
	s_add_i32 s47, s39, s28
	v_lshl_add_u64 v[154:155], s[24:25], 0, v[130:131]
	s_mov_b32 m0, s47
	ds_read_b128 v[192:195], v162 offset:16384
	ds_read_b128 v[196:199], v162 offset:17408
	ds_read_b128 v[200:203], v162 offset:18432
	ds_read_b128 v[204:207], v162 offset:19456
	ds_read_b128 v[208:211], v162 offset:20480
	ds_read_b128 v[212:215], v162 offset:21504
	ds_read_b128 v[216:219], v162 offset:22528
	ds_read_b128 v[220:223], v162 offset:23552
	global_load_lds_dwordx4 v[154:155], off
	s_add_i32 m0, s47, 0x2000
	s_add_u32 s48, s24, 0x40000
	v_lshl_add_u64 v[184:185], s[24:25], 0, v[134:135]
	s_addc_u32 s49, s25, 0
	s_add_i32 s47, s40, s28
	global_load_lds_dwordx4 v[184:185], off
	v_lshl_add_u64 v[224:225], s[48:49], 0, v[130:131]
	s_mov_b32 m0, s47
	v_lshl_add_u64 v[226:227], s[26:27], 0, v[132:133]
	global_load_lds_dwordx4 v[224:225], off
	v_lshl_add_u64 v[224:225], s[48:49], 0, v[134:135]
	s_add_i32 m0, s47, 0x2000
	s_nop 0
	global_load_lds_dwordx4 v[224:225], off
	v_lshl_add_u64 v[224:225], s[26:27], 0, v[128:129]
	s_mov_b32 m0, s31
	s_nop 0
	global_load_lds_dwordx4 v[224:225], off
	s_mov_b32 m0, s33
	s_nop 0
	global_load_lds_dwordx4 v[226:227], off
	s_waitcnt vmcnt(8)
	s_waitcnt lgkmcnt(0)
	s_barrier
; #define PG8_STAGE(bufoff, gbase, voff) do { _Pragma("unroll") for (int _i = 0; _i < 2; ++_i) \
;         __builtin_amdgcn_global_load_lds((const unsigned*)((const char*)(gbase) + (voff)[_i]), (PG8_LAS unsigned*)(lds + (bufoff) + ldsw + _i * 8192), 16, 0, 0); } while (0)
; #define PG8_LDA(dst, b, h) do { _Pragma("unroll") for (int m = 0; m < 4; ++m) _Pragma("unroll") for (int k = 0; k < 2; ++k) dst[m][k] = *(const PG8_LAS bf16x8*)(lds + PG8_SA(b, h) + aoff + m * 2048 + k * 1024); } while (0)
; #define PG8_LDB(dst, b, h) do { _Pragma("unroll") for (int n = 0; n < 2; ++n) _Pragma("unroll") for (int k = 0; k < 2; ++k) dst[n][k] = *(const PG8_LAS bf16x8*)(lds + PG8_SB(b, h) + boff + n * 2048 + k * 1024); } while (0)
; #define PG8_MMA(ai, bj, At, Bt) do { __builtin_amdgcn_s_setprio(1); _Pragma("unroll") for (int m = 0; m < 4; ++m) _Pragma("unroll") for (int n = 0; n < 2; ++n) _Pragma("unroll") for (int k = 0; k < 2; ++k) \
;         acc[ai][bj][m][n] = __builtin_amdgcn_mfma_f32_16x16x32_bf16(Bt[n][k], At[m][k], acc[ai][bj][m][n], 0, 0, 0); __builtin_amdgcn_s_setprio(0); } while (0)
; #define PG8_WAIT_V(n) asm volatile("s_waitcnt vmcnt(" #n ")" ::: "memory")
; #define PG8_WAIT_L(n) asm volatile("s_waitcnt lgkmcnt(" #n ")" ::: "memory")
; #define PG8_BAR __builtin_amdgcn_s_barrier()
; #define PG8_SCHED __builtin_amdgcn_sched_barrier(0)
; template <class Epi, class Sched, bool ALIGN_EPI = false, bool SP2 = false>
; __device__ __forceinline__ void gemm_phase(PG8_LAS unsigned char* lds, const Gemm g, const Sched& S, const Epi& E) {
;     ...
;             PG8_WAIT_V(8); PG8_WAIT_L(0); PG8_BAR; PG8_MMA(1, 0, At, B0); PG8_MMA(1, 1, At, B1); PG8_BAR; PG8_SCHED;
;             PG8_LDB(B0, 1, 0); PG8_LDB(B1, 1, 1); PG8_SCHED; PG8_LDA(At, 1, 0); PG8_STAGE(PG8_SA(0, 1), a2 + hstep, voffA);
;             PG8_WAIT_V(8); PG8_WAIT_L(0); PG8_BAR; PG8_MMA(0, 0, At, B0); PG8_MMA(0, 1, At, B1); PG8_BAR; PG8_SCHED;
	s_setprio 1
	s_waitcnt lgkmcnt(0)
	v_mfma_f32_16x16x32_bf16 v[60:63], v[146:149], v[192:195], 0
	v_mfma_f32_16x16x32_bf16 v[56:59], v[164:167], v[192:195], 0
	v_mfma_f32_16x16x32_bf16 v[44:47], v[146:149], v[200:203], 0
	v_mfma_f32_16x16x32_bf16 v[40:43], v[164:167], v[200:203], 0
	v_mfma_f32_16x16x32_bf16 v[28:31], v[146:149], v[208:211], 0
	v_mfma_f32_16x16x32_bf16 v[24:27], v[164:167], v[208:211], 0
	v_mfma_f32_16x16x32_bf16 v[12:15], v[146:149], v[216:219], 0
	v_mfma_f32_16x16x32_bf16 v[8:11], v[164:167], v[216:219], 0
	v_mfma_f32_16x16x32_bf16 v[60:63], v[150:153], v[196:199], v[60:63]
	v_mfma_f32_16x16x32_bf16 v[56:59], v[168:171], v[196:199], v[56:59]
	v_mfma_f32_16x16x32_bf16 v[44:47], v[150:153], v[204:207], v[44:47]
	v_mfma_f32_16x16x32_bf16 v[40:43], v[168:171], v[204:207], v[40:43]
	v_mfma_f32_16x16x32_bf16 v[28:31], v[150:153], v[212:215], v[28:31]
	v_mfma_f32_16x16x32_bf16 v[24:27], v[168:171], v[212:215], v[24:27]
	v_mfma_f32_16x16x32_bf16 v[12:15], v[150:153], v[220:223], v[12:15]
	v_mfma_f32_16x16x32_bf16 v[8:11], v[168:171], v[220:223], v[8:11]
	s_setprio 0
	s_setprio 1
	v_mfma_f32_16x16x32_bf16 v[52:55], v[172:175], v[192:195], 0
	v_mfma_f32_16x16x32_bf16 v[48:51], v[180:183], v[192:195], 0
	v_mfma_f32_16x16x32_bf16 v[36:39], v[172:175], v[200:203], 0
	v_mfma_f32_16x16x32_bf16 v[32:35], v[180:183], v[200:203], 0
	v_mfma_f32_16x16x32_bf16 v[20:23], v[172:175], v[208:211], 0
	v_mfma_f32_16x16x32_bf16 v[16:19], v[180:183], v[208:211], 0
	v_mfma_f32_16x16x32_bf16 v[4:7], v[172:175], v[216:219], 0
	v_mfma_f32_16x16x32_bf16 v[0:3], v[180:183], v[216:219], 0
	v_mfma_f32_16x16x32_bf16 v[52:55], v[176:179], v[196:199], v[52:55]
	v_mfma_f32_16x16x32_bf16 v[48:51], v[188:191], v[196:199], v[48:51]
	v_mfma_f32_16x16x32_bf16 v[36:39], v[176:179], v[204:207], v[36:39]
	v_mfma_f32_16x16x32_bf16 v[32:35], v[188:191], v[204:207], v[32:35]
	v_mfma_f32_16x16x32_bf16 v[20:23], v[176:179], v[212:215], v[20:23]
	v_mfma_f32_16x16x32_bf16 v[16:19], v[188:191], v[212:215], v[16:19]
	v_mfma_f32_16x16x32_bf16 v[4:7], v[176:179], v[220:223], v[4:7]
	v_mfma_f32_16x16x32_bf16 v[0:3], v[188:191], v[220:223], v[0:3]
	s_setprio 0
	s_barrier
	s_add_i32 s47, 0, 0x18000
	v_add_u32_e32 v136, s47, v157
	s_add_i32 s48, 0, 0x1c000
	ds_read_b128 v[146:149], v136
	ds_read_b128 v[150:153], v136 offset:1024
	ds_read_b128 v[164:167], v136 offset:2048
	ds_read_b128 v[168:171], v136 offset:3072
	v_add_u32_e32 v136, s48, v157
	ds_read_b128 v[172:175], v136
	ds_read_b128 v[176:179], v136 offset:1024
	ds_read_b128 v[180:183], v136 offset:2048
	ds_read_b128 v[188:191], v136 offset:3072
	s_add_u32 s26, s26, 0x40000
	s_addc_u32 s27, s27, 0
	s_mov_b32 m0, s34
	v_lshl_add_u64 v[228:229], s[26:27], 0, v[128:129]
	ds_read_b128 v[192:195], v162 offset:32768
	ds_read_b128 v[196:199], v162 offset:33792
	ds_read_b128 v[200:203], v162 offset:34816
	ds_read_b128 v[204:207], v162 offset:35840
	ds_read_b128 v[208:211], v162 offset:36864
	ds_read_b128 v[212:215], v162 offset:37888
	ds_read_b128 v[216:219], v162 offset:38912
	ds_read_b128 v[220:223], v162 offset:39936
	global_load_lds_dwordx4 v[228:229], off
	v_lshl_add_u64 v[228:229], s[26:27], 0, v[132:133]
	s_mov_b32 m0, s35
	s_nop 0
	global_load_lds_dwordx4 v[228:229], off
	s_waitcnt vmcnt(8)
	s_waitcnt lgkmcnt(0)
	s_barrier
	s_setprio 1
	s_waitcnt lgkmcnt(0)
	v_mfma_f32_16x16x32_bf16 v[124:127], v[146:149], v[192:195], v[124:127]
	v_mfma_f32_16x16x32_bf16 v[120:123], v[164:167], v[192:195], v[120:123]
	v_mfma_f32_16x16x32_bf16 v[108:111], v[146:149], v[200:203], v[108:111]
	v_mfma_f32_16x16x32_bf16 v[104:107], v[164:167], v[200:203], v[104:107]
	v_mfma_f32_16x16x32_bf16 v[92:95], v[146:149], v[208:211], v[92:95]
	v_mfma_f32_16x16x32_bf16 v[88:91], v[164:167], v[208:211], v[88:91]
	v_mfma_f32_16x16x32_bf16 v[76:79], v[146:149], v[216:219], v[76:79]
	v_mfma_f32_16x16x32_bf16 v[72:75], v[164:167], v[216:219], v[72:75]
	v_mfma_f32_16x16x32_bf16 v[124:127], v[150:153], v[196:199], v[124:127]
	v_mfma_f32_16x16x32_bf16 v[120:123], v[168:171], v[196:199], v[120:123]
	v_mfma_f32_16x16x32_bf16 v[108:111], v[150:153], v[204:207], v[108:111]
	v_mfma_f32_16x16x32_bf16 v[104:107], v[168:171], v[204:207], v[104:107]
	v_mfma_f32_16x16x32_bf16 v[92:95], v[150:153], v[212:215], v[92:95]
	v_mfma_f32_16x16x32_bf16 v[88:91], v[168:171], v[212:215], v[88:91]
	v_mfma_f32_16x16x32_bf16 v[76:79], v[150:153], v[220:223], v[76:79]
	v_mfma_f32_16x16x32_bf16 v[72:75], v[168:171], v[220:223], v[72:75]
	s_setprio 0
	s_setprio 1
	v_mfma_f32_16x16x32_bf16 v[116:119], v[172:175], v[192:195], v[116:119]
	v_mfma_f32_16x16x32_bf16 v[112:115], v[180:183], v[192:195], v[112:115]
	v_mfma_f32_16x16x32_bf16 v[100:103], v[172:175], v[200:203], v[100:103]
	v_mfma_f32_16x16x32_bf16 v[96:99], v[180:183], v[200:203], v[96:99]
	v_mfma_f32_16x16x32_bf16 v[84:87], v[172:175], v[208:211], v[84:87]
	v_mfma_f32_16x16x32_bf16 v[80:83], v[180:183], v[208:211], v[80:83]
	v_mfma_f32_16x16x32_bf16 v[68:71], v[172:175], v[216:219], v[68:71]
	v_mfma_f32_16x16x32_bf16 v[64:67], v[180:183], v[216:219], v[64:67]
	v_mfma_f32_16x16x32_bf16 v[116:119], v[176:179], v[196:199], v[116:119]
	v_mfma_f32_16x16x32_bf16 v[112:115], v[188:191], v[196:199], v[112:115]
	v_mfma_f32_16x16x32_bf16 v[100:103], v[176:179], v[204:207], v[100:103]
	v_mfma_f32_16x16x32_bf16 v[96:99], v[188:191], v[204:207], v[96:99]
	v_mfma_f32_16x16x32_bf16 v[84:87], v[176:179], v[212:215], v[84:87]
	v_mfma_f32_16x16x32_bf16 v[80:83], v[188:191], v[212:215], v[80:83]
	v_mfma_f32_16x16x32_bf16 v[68:71], v[176:179], v[220:223], v[68:71]
	v_mfma_f32_16x16x32_bf16 v[64:67], v[188:191], v[220:223], v[64:67]
	s_setprio 0
	s_barrier
; #define PG8_STAGE(bufoff, gbase, voff) do { _Pragma("unroll") for (int _i = 0; _i < 2; ++_i) \
;         __builtin_amdgcn_global_load_lds((const unsigned*)((const char*)(gbase) + (voff)[_i]), (PG8_LAS unsigned*)(lds + (bufoff) + ldsw + _i * 8192), 16, 0, 0); } while (0)
; #define PG8_LDA(dst, b, h) do { _Pragma("unroll") for (int m = 0; m < 4; ++m) _Pragma("unroll") for (int k = 0; k < 2; ++k) dst[m][k] = *(const PG8_LAS bf16x8*)(lds + PG8_SA(b, h) + aoff + m * 2048 + k * 1024); } while (0)
; #define PG8_MMA(ai, bj, At, Bt) do { __builtin_amdgcn_s_setprio(1); _Pragma("unroll") for (int m = 0; m < 4; ++m) _Pragma("unroll") for (int n = 0; n < 2; ++n) _Pragma("unroll") for (int k = 0; k < 2; ++k) \
;         acc[ai][bj][m][n] = __builtin_amdgcn_mfma_f32_16x16x32_bf16(Bt[n][k], At[m][k], acc[ai][bj][m][n], 0, 0, 0); __builtin_amdgcn_s_setprio(0); } while (0)
; #define PG8_WAIT_V(n) asm volatile("s_waitcnt vmcnt(" #n ")" ::: "memory")
; #define PG8_WAIT_L(n) asm volatile("s_waitcnt lgkmcnt(" #n ")" ::: "memory")
; #define PG8_BAR __builtin_amdgcn_s_barrier()
; #define PG8_SCHED __builtin_amdgcn_sched_barrier(0)
; template <class Epi, class Sched, bool ALIGN_EPI = false, bool SP2 = false>
; __device__ __forceinline__ void gemm_phase(PG8_LAS unsigned char* lds, const Gemm g, const Sched& S, const Epi& E) {
;     ...
;             PG8_LDA(At, 1, 1); PG8_STAGE(PG8_SB(1, 0), b3, voffB); PG8_STAGE(PG8_SB(1, 1), b3 + hstep, voffB); PG8_STAGE(PG8_SA(1, 0), a3, voffA);
;             PG8_WAIT_V(8); PG8_WAIT_L(0); PG8_BAR; PG8_MMA(1, 0, At, B0); PG8_MMA(1, 1, At, B1); PG8_BAR; PG8_SCHED;
	s_add_i32 s26, s47, s28
	v_lshl_add_u64 v[154:155], v[154:155], 0, s[8:9]
	s_mov_b32 m0, s26
	ds_read_b128 v[192:195], v162 offset:49152
	ds_read_b128 v[196:199], v162 offset:50176
	ds_read_b128 v[200:203], v162 offset:51200
	ds_read_b128 v[204:207], v162 offset:52224
	ds_read_b128 v[208:211], v162 offset:53248
	ds_read_b128 v[212:215], v162 offset:54272
	ds_read_b128 v[216:219], v162 offset:55296
	ds_read_b128 v[220:223], v162 offset:56320
	global_load_lds_dwordx4 v[154:155], off
	s_add_i32 m0, s26, 0x2000
	s_add_u32 s24, s24, 0x40080
	v_lshl_add_u64 v[154:155], v[184:185], 0, s[8:9]
	s_addc_u32 s25, s25, 0
	s_add_i32 s26, s48, s28
	global_load_lds_dwordx4 v[154:155], off
	v_lshl_add_u64 v[154:155], s[24:25], 0, v[130:131]
	s_mov_b32 m0, s26
	s_nop 0
	global_load_lds_dwordx4 v[154:155], off
	v_lshl_add_u64 v[154:155], s[24:25], 0, v[134:135]
	s_add_i32 m0, s26, 0x2000
	s_nop 0
	global_load_lds_dwordx4 v[154:155], off
	v_lshl_add_u64 v[154:155], v[224:225], 0, s[8:9]
	s_mov_b32 m0, s36
	s_nop 0
	global_load_lds_dwordx4 v[154:155], off
	v_lshl_add_u64 v[154:155], v[226:227], 0, s[8:9]
	s_mov_b32 m0, s37
	s_nop 0
	global_load_lds_dwordx4 v[154:155], off
	s_waitcnt vmcnt(8)
	s_waitcnt lgkmcnt(0)
	s_barrier
	s_setprio 1
	s_waitcnt lgkmcnt(0)
	v_mfma_f32_16x16x32_bf16 v[60:63], v[146:149], v[192:195], v[60:63]
	v_mfma_f32_16x16x32_bf16 v[56:59], v[164:167], v[192:195], v[56:59]
	v_mfma_f32_16x16x32_bf16 v[44:47], v[146:149], v[200:203], v[44:47]
	v_mfma_f32_16x16x32_bf16 v[40:43], v[164:167], v[200:203], v[40:43]
	v_mfma_f32_16x16x32_bf16 v[28:31], v[146:149], v[208:211], v[28:31]
	v_mfma_f32_16x16x32_bf16 v[24:27], v[164:167], v[208:211], v[24:27]
	v_mfma_f32_16x16x32_bf16 v[12:15], v[146:149], v[216:219], v[12:15]
	v_mfma_f32_16x16x32_bf16 v[8:11], v[164:167], v[216:219], v[8:11]
	v_mfma_f32_16x16x32_bf16 v[60:63], v[150:153], v[196:199], v[60:63]
	v_mfma_f32_16x16x32_bf16 v[56:59], v[168:171], v[196:199], v[56:59]
	v_mfma_f32_16x16x32_bf16 v[44:47], v[150:153], v[204:207], v[44:47]
	v_mfma_f32_16x16x32_bf16 v[40:43], v[168:171], v[204:207], v[40:43]
	v_mfma_f32_16x16x32_bf16 v[28:31], v[150:153], v[212:215], v[28:31]
	v_mfma_f32_16x16x32_bf16 v[24:27], v[168:171], v[212:215], v[24:27]
	v_mfma_f32_16x16x32_bf16 v[12:15], v[150:153], v[220:223], v[12:15]
	v_mfma_f32_16x16x32_bf16 v[8:11], v[168:171], v[220:223], v[8:11]
	s_setprio 0
	s_setprio 1
	v_mfma_f32_16x16x32_bf16 v[52:55], v[172:175], v[192:195], v[52:55]
	v_mfma_f32_16x16x32_bf16 v[48:51], v[180:183], v[192:195], v[48:51]
	v_mfma_f32_16x16x32_bf16 v[36:39], v[172:175], v[200:203], v[36:39]
	v_mfma_f32_16x16x32_bf16 v[32:35], v[180:183], v[200:203], v[32:35]
	v_mfma_f32_16x16x32_bf16 v[20:23], v[172:175], v[208:211], v[20:23]
	v_mfma_f32_16x16x32_bf16 v[16:19], v[180:183], v[208:211], v[16:19]
	v_mfma_f32_16x16x32_bf16 v[4:7], v[172:175], v[216:219], v[4:7]
	v_mfma_f32_16x16x32_bf16 v[0:3], v[180:183], v[216:219], v[0:3]
	v_mfma_f32_16x16x32_bf16 v[52:55], v[176:179], v[196:199], v[52:55]
	v_mfma_f32_16x16x32_bf16 v[48:51], v[188:191], v[196:199], v[48:51]
	v_mfma_f32_16x16x32_bf16 v[36:39], v[176:179], v[204:207], v[36:39]
	v_mfma_f32_16x16x32_bf16 v[32:35], v[188:191], v[204:207], v[32:35]
	v_mfma_f32_16x16x32_bf16 v[20:23], v[176:179], v[212:215], v[20:23]
	v_mfma_f32_16x16x32_bf16 v[16:19], v[188:191], v[212:215], v[16:19]
	v_mfma_f32_16x16x32_bf16 v[4:7], v[176:179], v[220:223], v[4:7]
	v_mfma_f32_16x16x32_bf16 v[0:3], v[188:191], v[220:223], v[0:3]
	s_setprio 0
	s_barrier
	s_add_i32 s46, s46, 2
	s_add_u32 s22, s22, 0x100
	s_addc_u32 s23, s23, 0
	s_add_u32 s44, s44, 0x100
	s_addc_u32 s45, s45, 0
	s_cmp_gt_u32 s46, 13

;     __device__ __forceinline__ bool next(int i, Unit& u) const { if (!base.next(i >> 1, u)) return false; if (i & 1) { u.pm += 64; u.pn += 8; } return true; }
; #define PG8_STAGE(bufoff, gbase, voff) do { _Pragma("unroll") for (int _i = 0; _i < 2; ++_i) \
;         __builtin_amdgcn_global_load_lds((const unsigned*)((const char*)(gbase) + (voff)[_i]), (PG8_LAS unsigned*)(lds + (bufoff) + ldsw + _i * 8192), 16, 0, 0); } while (0)
; #define PG8_LDA(dst, b, h) do { _Pragma("unroll") for (int m = 0; m < 4; ++m) _Pragma("unroll") for (int k = 0; k < 2; ++k) dst[m][k] = *(const PG8_LAS bf16x8*)(lds + PG8_SA(b, h) + aoff + m * 2048 + k * 1024); } while (0)
; #define PG8_LDB(dst, b, h) do { _Pragma("unroll") for (int n = 0; n < 2; ++n) _Pragma("unroll") for (int k = 0; k < 2; ++k) dst[n][k] = *(const PG8_LAS bf16x8*)(lds + PG8_SB(b, h) + boff + n * 2048 + k * 1024); } while (0)
; #define PG8_WAIT_V(n) asm volatile("s_waitcnt vmcnt(" #n ")" ::: "memory")
; #define PG8_WAIT_L(n) asm volatile("s_waitcnt lgkmcnt(" #n ")" ::: "memory")
; #define PG8_BAR __builtin_amdgcn_s_barrier()
; #define PG8_SCHED __builtin_amdgcn_sched_barrier(0)
; template <class Epi, class Sched, bool ALIGN_EPI = false, bool SP2 = false>
; __device__ __forceinline__ void gemm_phase(PG8_LAS unsigned char* lds, const Gemm g, const Sched& S, const Epi& E) {
;     ...
;         const bool has_next = S.next(ui + 1, nxt);
;         const char* nA = has_next ? (const char*)g.A + (size_t)nxt.pm * tstep : cA; const char* nB = has_next ? (const char*)g.Bt + (size_t)nxt.pn * tstep : cB;
;         for (int t = 0; t < nt; t += 2) {
;             const bool last = (t == nt - 2);
;             const char* a1 = cA + (size_t)(t + 1) * kstep;
;             const char* a2 = last ? nA : cA + (size_t)(t + 2) * kstep; const char* b2 = last ? nB : cB + (size_t)(t + 2) * kstep;
;             const char* a3 = a2 + kstep; const char* b3 = b2 + kstep;
;             if (last && has_next) S.a_ready(nxt);
;             if constexpr (SP2) {
;             PG8_LDB(B0, 0, 0); PG8_LDB(B1, 0, 1); PG8_SCHED; PG8_LDA(At, 0, 0); PG8_STAGE(PG8_SA(1, 1), a1 + hstep, voffA);
;             PG8_WAIT_V(8); PG8_WAIT_L(0); PG8_BAR; PG8_MMA(0, 0, At, B0); PG8_MMA(0, 1, At, B1); PG8_BAR; PG8_SCHED;
;             PG8_LDA(At, 0, 1); PG8_STAGE(PG8_SB(0, 0), b2, voffB); PG8_STAGE(PG8_SB(0, 1), b2 + hstep, voffB); PG8_STAGE(PG8_SA(0, 0), a2, voffA);
.LBB0_893:
	s_ashr_i32 s25, s24, 31
	s_lshl_b64 s[28:29], s[24:25], 20
	v_readlane_b32 s30, v236, 50
	v_readlane_b32 s31, v236, 51
	s_add_u32 s28, s30, s28
	s_addc_u32 s29, s31, s29
	s_and_b64 s[30:31], s[6:7], exec
	s_cselect_b32 s25, s29, s39
	s_cselect_b32 s35, s28, s38
	s_ashr_i32 s27, s26, 31
	s_lshl_b64 s[30:31], s[26:27], 20
	v_readlane_b32 s42, v236, 43
	v_readlane_b32 s43, v236, 44
	s_add_u32 s30, s42, s30
	s_addc_u32 s31, s43, s31
	s_and_b64 s[42:43], s[6:7], exec
	s_cselect_b32 s27, s31, s41
	s_cselect_b32 s55, s30, s40
	s_add_u32 s38, s38, 0x80080
	s_addc_u32 s39, s39, 0
	s_add_u32 s56, s40, 0x100
	s_addc_u32 s57, s41, 0
	s_mov_b32 s58, -2
	s_waitcnt lgkmcnt(0)
	ds_read_b128 v[72:75], v169
	ds_read_b128 v[84:87], v169 offset:1024
	ds_read_b128 v[92:95], v169 offset:2048
	ds_read_b128 v[96:99], v169 offset:3072
	ds_read_b128 v[156:159], v170
	ds_read_b128 v[160:163], v170 offset:1024
	ds_read_b128 v[174:177], v170 offset:2048
	ds_read_b128 v[178:181], v170 offset:3072
	s_add_u32 s40, s38, 0xfff80080
	s_addc_u32 s41, s39, -1
	s_cmp_eq_u32 s58, 28
	s_cselect_b32 s43, s25, s41
	s_cselect_b32 s42, s35, s40
	s_cselect_b32 s41, s27, s57
	s_cselect_b32 s40, s55, s56
	v_lshl_add_u64 v[164:165], s[38:39], 0, v[148:149]
	s_add_i32 m0, s37, 0xc000
	ds_read_b128 v[182:185], v171
	ds_read_b128 v[188:191], v171 offset:1024
	ds_read_b128 v[192:195], v171 offset:2048
	ds_read_b128 v[196:199], v171 offset:3072
	ds_read_b128 v[200:203], v171 offset:4096
	ds_read_b128 v[204:207], v171 offset:5120
	ds_read_b128 v[208:211], v171 offset:6144
	ds_read_b128 v[212:215], v171 offset:7168
	global_load_lds_dwordx4 v[164:165], off
	v_lshl_add_u64 v[164:165], s[38:39], 0, v[150:151]
	s_add_i32 m0, s37, 0xe000
	s_nop 0
	global_load_lds_dwordx4 v[164:165], off
	s_waitcnt vmcnt(8)
	s_waitcnt lgkmcnt(0)
	s_barrier
	s_setprio 1
	s_waitcnt lgkmcnt(0)
	v_mfma_f32_16x16x32_bf16 v[140:143], v[72:75], v[182:185], 0
	v_mfma_f32_16x16x32_bf16 v[136:139], v[92:95], v[182:185], 0
	v_mfma_f32_16x16x32_bf16 v[124:127], v[72:75], v[192:195], 0
	v_mfma_f32_16x16x32_bf16 v[120:123], v[92:95], v[192:195], 0
	v_mfma_f32_16x16x32_bf16 v[108:111], v[72:75], v[200:203], 0
	v_mfma_f32_16x16x32_bf16 v[104:107], v[92:95], v[200:203], 0
	v_mfma_f32_16x16x32_bf16 v[80:83], v[72:75], v[208:211], 0
	v_mfma_f32_16x16x32_bf16 v[76:79], v[92:95], v[208:211], 0
	v_mfma_f32_16x16x32_bf16 v[140:143], v[84:87], v[188:191], v[140:143]
	v_mfma_f32_16x16x32_bf16 v[136:139], v[96:99], v[188:191], v[136:139]
	v_mfma_f32_16x16x32_bf16 v[124:127], v[84:87], v[196:199], v[124:127]
	v_mfma_f32_16x16x32_bf16 v[120:123], v[96:99], v[196:199], v[120:123]
	v_mfma_f32_16x16x32_bf16 v[108:111], v[84:87], v[204:207], v[108:111]
	v_mfma_f32_16x16x32_bf16 v[104:107], v[96:99], v[204:207], v[104:107]
	v_mfma_f32_16x16x32_bf16 v[80:83], v[84:87], v[212:215], v[80:83]
	v_mfma_f32_16x16x32_bf16 v[76:79], v[96:99], v[212:215], v[76:79]
	s_setprio 0
	s_setprio 1
	v_mfma_f32_16x16x32_bf16 v[132:135], v[156:159], v[182:185], 0
	v_mfma_f32_16x16x32_bf16 v[128:131], v[174:177], v[182:185], 0
	v_mfma_f32_16x16x32_bf16 v[116:119], v[156:159], v[192:195], 0
	v_mfma_f32_16x16x32_bf16 v[112:115], v[174:177], v[192:195], 0
	v_mfma_f32_16x16x32_bf16 v[100:103], v[156:159], v[200:203], 0
	v_mfma_f32_16x16x32_bf16 v[88:91], v[174:177], v[200:203], 0
	v_mfma_f32_16x16x32_bf16 v[68:71], v[156:159], v[208:211], 0
	v_mfma_f32_16x16x32_bf16 v[64:67], v[174:177], v[208:211], 0
	v_mfma_f32_16x16x32_bf16 v[132:135], v[160:163], v[188:191], v[132:135]
	v_mfma_f32_16x16x32_bf16 v[128:131], v[178:181], v[188:191], v[128:131]
	v_mfma_f32_16x16x32_bf16 v[116:119], v[160:163], v[196:199], v[116:119]
	v_mfma_f32_16x16x32_bf16 v[112:115], v[178:181], v[196:199], v[112:115]
	v_mfma_f32_16x16x32_bf16 v[100:103], v[160:163], v[204:207], v[100:103]
	v_mfma_f32_16x16x32_bf16 v[88:91], v[178:181], v[204:207], v[88:91]
	v_mfma_f32_16x16x32_bf16 v[68:71], v[160:163], v[212:215], v[68:71]
	v_mfma_f32_16x16x32_bf16 v[64:67], v[178:181], v[212:215], v[64:67]
	s_setprio 0
	s_barrier
	s_add_i32 s59, s53, s33
	v_lshl_add_u64 v[164:165], s[40:41], 0, v[144:145]
	s_mov_b32 m0, s59
	ds_read_b128 v[182:185], v171 offset:16384
	ds_read_b128 v[188:191], v171 offset:17408
	ds_read_b128 v[192:195], v171 offset:18432
	ds_read_b128 v[196:199], v171 offset:19456
	ds_read_b128 v[200:203], v171 offset:20480
	ds_read_b128 v[204:207], v171 offset:21504
	ds_read_b128 v[208:211], v171 offset:22528
	ds_read_b128 v[212:215], v171 offset:23552
	global_load_lds_dwordx4 v[164:165], off
	s_add_i32 m0, s59, 0x2000
	s_add_u32 s60, s40, 0x80000
	v_lshl_add_u64 v[216:217], s[40:41], 0, v[146:147]
	s_addc_u32 s61, s41, 0
	s_add_i32 s59, s54, s33
	global_load_lds_dwordx4 v[216:217], off
	v_lshl_add_u64 v[218:219], s[60:61], 0, v[144:145]
	s_mov_b32 m0, s59
	v_lshl_add_u64 v[220:221], s[42:43], 0, v[146:147]
	global_load_lds_dwordx4 v[218:219], off
	v_lshl_add_u64 v[218:219], s[60:61], 0, v[146:147]
	s_add_i32 m0, s59, 0x2000
	s_nop 0
	global_load_lds_dwordx4 v[218:219], off
	v_lshl_add_u64 v[218:219], s[42:43], 0, v[144:145]
	s_mov_b32 m0, s37
	s_nop 0
	global_load_lds_dwordx4 v[218:219], off
	s_mov_b32 m0, s44
	s_nop 0
	global_load_lds_dwordx4 v[220:221], off
	s_waitcnt vmcnt(8)
	s_waitcnt lgkmcnt(0)
	s_barrier
; #define PG8_STAGE(bufoff, gbase, voff) do { _Pragma("unroll") for (int _i = 0; _i < 2; ++_i) \
;         __builtin_amdgcn_global_load_lds((const unsigned*)((const char*)(gbase) + (voff)[_i]), (PG8_LAS unsigned*)(lds + (bufoff) + ldsw + _i * 8192), 16, 0, 0); } while (0)
; #define PG8_LDA(dst, b, h) do { _Pragma("unroll") for (int m = 0; m < 4; ++m) _Pragma("unroll") for (int k = 0; k < 2; ++k) dst[m][k] = *(const PG8_LAS bf16x8*)(lds + PG8_SA(b, h) + aoff + m * 2048 + k * 1024); } while (0)
; #define PG8_LDB(dst, b, h) do { _Pragma("unroll") for (int n = 0; n < 2; ++n) _Pragma("unroll") for (int k = 0; k < 2; ++k) dst[n][k] = *(const PG8_LAS bf16x8*)(lds + PG8_SB(b, h) + boff + n * 2048 + k * 1024); } while (0)
; #define PG8_MMA(ai, bj, At, Bt) do { __builtin_amdgcn_s_setprio(1); _Pragma("unroll") for (int m = 0; m < 4; ++m) _Pragma("unroll") for (int n = 0; n < 2; ++n) _Pragma("unroll") for (int k = 0; k < 2; ++k) \
;         acc[ai][bj][m][n] = __builtin_amdgcn_mfma_f32_16x16x32_bf16(Bt[n][k], At[m][k], acc[ai][bj][m][n], 0, 0, 0); __builtin_amdgcn_s_setprio(0); } while (0)
; #define PG8_WAIT_V(n) asm volatile("s_waitcnt vmcnt(" #n ")" ::: "memory")
; #define PG8_WAIT_L(n) asm volatile("s_waitcnt lgkmcnt(" #n ")" ::: "memory")
; #define PG8_BAR __builtin_amdgcn_s_barrier()
; #define PG8_SCHED __builtin_amdgcn_sched_barrier(0)
; template <class Epi, class Sched, bool ALIGN_EPI = false, bool SP2 = false>
; __device__ __forceinline__ void gemm_phase(PG8_LAS unsigned char* lds, const Gemm g, const Sched& S, const Epi& E) {
;     ...
;             PG8_WAIT_V(8); PG8_WAIT_L(0); PG8_BAR; PG8_MMA(1, 0, At, B0); PG8_MMA(1, 1, At, B1); PG8_BAR; PG8_SCHED;
;             PG8_LDB(B0, 1, 0); PG8_LDB(B1, 1, 1); PG8_SCHED; PG8_LDA(At, 1, 0); PG8_STAGE(PG8_SA(0, 1), a2 + hstep, voffA);
;             PG8_WAIT_V(8); PG8_WAIT_L(0); PG8_BAR; PG8_MMA(0, 0, At, B0); PG8_MMA(0, 1, At, B1); PG8_BAR; PG8_SCHED;
	s_setprio 1
	s_waitcnt lgkmcnt(0)
	v_mfma_f32_16x16x32_bf16 v[60:63], v[72:75], v[182:185], 0
	v_mfma_f32_16x16x32_bf16 v[56:59], v[92:95], v[182:185], 0
	v_mfma_f32_16x16x32_bf16 v[44:47], v[72:75], v[192:195], 0
	v_mfma_f32_16x16x32_bf16 v[40:43], v[92:95], v[192:195], 0
	v_mfma_f32_16x16x32_bf16 v[28:31], v[72:75], v[200:203], 0
	v_mfma_f32_16x16x32_bf16 v[24:27], v[92:95], v[200:203], 0
	v_mfma_f32_16x16x32_bf16 v[12:15], v[72:75], v[208:211], 0
	v_mfma_f32_16x16x32_bf16 v[8:11], v[92:95], v[208:211], 0
	v_mfma_f32_16x16x32_bf16 v[60:63], v[84:87], v[188:191], v[60:63]
	v_mfma_f32_16x16x32_bf16 v[56:59], v[96:99], v[188:191], v[56:59]
	v_mfma_f32_16x16x32_bf16 v[44:47], v[84:87], v[196:199], v[44:47]
	v_mfma_f32_16x16x32_bf16 v[40:43], v[96:99], v[196:199], v[40:43]
	v_mfma_f32_16x16x32_bf16 v[28:31], v[84:87], v[204:207], v[28:31]
	v_mfma_f32_16x16x32_bf16 v[24:27], v[96:99], v[204:207], v[24:27]
	v_mfma_f32_16x16x32_bf16 v[12:15], v[84:87], v[212:215], v[12:15]
	v_mfma_f32_16x16x32_bf16 v[8:11], v[96:99], v[212:215], v[8:11]
	s_setprio 0
	s_setprio 1
	v_mfma_f32_16x16x32_bf16 v[52:55], v[156:159], v[182:185], 0
	v_mfma_f32_16x16x32_bf16 v[48:51], v[174:177], v[182:185], 0
	v_mfma_f32_16x16x32_bf16 v[36:39], v[156:159], v[192:195], 0
	v_mfma_f32_16x16x32_bf16 v[32:35], v[174:177], v[192:195], 0
	v_mfma_f32_16x16x32_bf16 v[20:23], v[156:159], v[200:203], 0
	v_mfma_f32_16x16x32_bf16 v[16:19], v[174:177], v[200:203], 0
	v_mfma_f32_16x16x32_bf16 v[4:7], v[156:159], v[208:211], 0
	v_mfma_f32_16x16x32_bf16 v[0:3], v[174:177], v[208:211], 0
	v_mfma_f32_16x16x32_bf16 v[52:55], v[160:163], v[188:191], v[52:55]
	v_mfma_f32_16x16x32_bf16 v[48:51], v[178:181], v[188:191], v[48:51]
	v_mfma_f32_16x16x32_bf16 v[36:39], v[160:163], v[196:199], v[36:39]
	v_mfma_f32_16x16x32_bf16 v[32:35], v[178:181], v[196:199], v[32:35]
	v_mfma_f32_16x16x32_bf16 v[20:23], v[160:163], v[204:207], v[20:23]
	v_mfma_f32_16x16x32_bf16 v[16:19], v[178:181], v[204:207], v[16:19]
	v_mfma_f32_16x16x32_bf16 v[4:7], v[160:163], v[212:215], v[4:7]
	v_mfma_f32_16x16x32_bf16 v[0:3], v[178:181], v[212:215], v[0:3]
	s_setprio 0
	s_barrier
	s_add_i32 s59, 0, 0x18000
	s_add_i32 s60, 0, 0x1c000
	v_add_u32_e32 v96, s59, v167
	v_add_u32_e32 v173, s60, v167
	ds_read_b128 v[72:75], v96
	ds_read_b128 v[84:87], v96 offset:1024
	ds_read_b128 v[92:95], v96 offset:2048
	ds_read_b128 v[96:99], v96 offset:3072
	ds_read_b128 v[156:159], v173
	ds_read_b128 v[160:163], v173 offset:1024
	ds_read_b128 v[174:177], v173 offset:2048
	ds_read_b128 v[178:181], v173 offset:3072
	s_add_u32 s42, s42, 0x80000
	s_addc_u32 s43, s43, 0
	s_mov_b32 m0, s45
	v_lshl_add_u64 v[222:223], s[42:43], 0, v[144:145]
	ds_read_b128 v[182:185], v171 offset:32768
	ds_read_b128 v[188:191], v171 offset:33792
	ds_read_b128 v[192:195], v171 offset:34816
	ds_read_b128 v[196:199], v171 offset:35840
	ds_read_b128 v[200:203], v171 offset:36864
	ds_read_b128 v[204:207], v171 offset:37888
	ds_read_b128 v[208:211], v171 offset:38912
	ds_read_b128 v[212:215], v171 offset:39936
	global_load_lds_dwordx4 v[222:223], off
	v_lshl_add_u64 v[222:223], s[42:43], 0, v[146:147]
	s_mov_b32 m0, s46
	s_nop 0
	global_load_lds_dwordx4 v[222:223], off
	s_waitcnt vmcnt(8)
	s_waitcnt lgkmcnt(0)
	s_barrier
	s_setprio 1
	s_waitcnt lgkmcnt(0)
	v_mfma_f32_16x16x32_bf16 v[140:143], v[72:75], v[182:185], v[140:143]
	v_mfma_f32_16x16x32_bf16 v[136:139], v[92:95], v[182:185], v[136:139]
	v_mfma_f32_16x16x32_bf16 v[124:127], v[72:75], v[192:195], v[124:127]
	v_mfma_f32_16x16x32_bf16 v[120:123], v[92:95], v[192:195], v[120:123]
	v_mfma_f32_16x16x32_bf16 v[108:111], v[72:75], v[200:203], v[108:111]
	v_mfma_f32_16x16x32_bf16 v[104:107], v[92:95], v[200:203], v[104:107]
	v_mfma_f32_16x16x32_bf16 v[80:83], v[72:75], v[208:211], v[80:83]
	v_mfma_f32_16x16x32_bf16 v[76:79], v[92:95], v[208:211], v[76:79]
	v_mfma_f32_16x16x32_bf16 v[140:143], v[84:87], v[188:191], v[140:143]
	v_mfma_f32_16x16x32_bf16 v[136:139], v[96:99], v[188:191], v[136:139]
	v_mfma_f32_16x16x32_bf16 v[124:127], v[84:87], v[196:199], v[124:127]
	v_mfma_f32_16x16x32_bf16 v[120:123], v[96:99], v[196:199], v[120:123]
	v_mfma_f32_16x16x32_bf16 v[108:111], v[84:87], v[204:207], v[108:111]
	v_mfma_f32_16x16x32_bf16 v[104:107], v[96:99], v[204:207], v[104:107]
	v_mfma_f32_16x16x32_bf16 v[80:83], v[84:87], v[212:215], v[80:83]
	v_mfma_f32_16x16x32_bf16 v[76:79], v[96:99], v[212:215], v[76:79]
	s_setprio 0
	s_setprio 1
	v_mfma_f32_16x16x32_bf16 v[132:135], v[156:159], v[182:185], v[132:135]
	v_mfma_f32_16x16x32_bf16 v[128:131], v[174:177], v[182:185], v[128:131]
	v_mfma_f32_16x16x32_bf16 v[116:119], v[156:159], v[192:195], v[116:119]
	v_mfma_f32_16x16x32_bf16 v[112:115], v[174:177], v[192:195], v[112:115]
	v_mfma_f32_16x16x32_bf16 v[100:103], v[156:159], v[200:203], v[100:103]
	v_mfma_f32_16x16x32_bf16 v[88:91], v[174:177], v[200:203], v[88:91]
	v_mfma_f32_16x16x32_bf16 v[68:71], v[156:159], v[208:211], v[68:71]
	v_mfma_f32_16x16x32_bf16 v[64:67], v[174:177], v[208:211], v[64:67]
	v_mfma_f32_16x16x32_bf16 v[132:135], v[160:163], v[188:191], v[132:135]
	v_mfma_f32_16x16x32_bf16 v[128:131], v[178:181], v[188:191], v[128:131]
	v_mfma_f32_16x16x32_bf16 v[116:119], v[160:163], v[196:199], v[116:119]
	v_mfma_f32_16x16x32_bf16 v[112:115], v[178:181], v[196:199], v[112:115]
	v_mfma_f32_16x16x32_bf16 v[100:103], v[160:163], v[204:207], v[100:103]
	v_mfma_f32_16x16x32_bf16 v[88:91], v[178:181], v[204:207], v[88:91]
	v_mfma_f32_16x16x32_bf16 v[68:71], v[160:163], v[212:215], v[68:71]
	v_mfma_f32_16x16x32_bf16 v[64:67], v[178:181], v[212:215], v[64:67]
	s_setprio 0
	s_barrier
; #define PG8_STAGE(bufoff, gbase, voff) do { _Pragma("unroll") for (int _i = 0; _i < 2; ++_i) \
;         __builtin_amdgcn_global_load_lds((const unsigned*)((const char*)(gbase) + (voff)[_i]), (PG8_LAS unsigned*)(lds + (bufoff) + ldsw + _i * 8192), 16, 0, 0); } while (0)
; #define PG8_LDA(dst, b, h) do { _Pragma("unroll") for (int m = 0; m < 4; ++m) _Pragma("unroll") for (int k = 0; k < 2; ++k) dst[m][k] = *(const PG8_LAS bf16x8*)(lds + PG8_SA(b, h) + aoff + m * 2048 + k * 1024); } while (0)
; #define PG8_MMA(ai, bj, At, Bt) do { __builtin_amdgcn_s_setprio(1); _Pragma("unroll") for (int m = 0; m < 4; ++m) _Pragma("unroll") for (int n = 0; n < 2; ++n) _Pragma("unroll") for (int k = 0; k < 2; ++k) \
;         acc[ai][bj][m][n] = __builtin_amdgcn_mfma_f32_16x16x32_bf16(Bt[n][k], At[m][k], acc[ai][bj][m][n], 0, 0, 0); __builtin_amdgcn_s_setprio(0); } while (0)
; #define PG8_WAIT_V(n) asm volatile("s_waitcnt vmcnt(" #n ")" ::: "memory")
; #define PG8_WAIT_L(n) asm volatile("s_waitcnt lgkmcnt(" #n ")" ::: "memory")
; #define PG8_BAR __builtin_amdgcn_s_barrier()
; #define PG8_SCHED __builtin_amdgcn_sched_barrier(0)
; template <class Epi, class Sched, bool ALIGN_EPI = false, bool SP2 = false>
; __device__ __forceinline__ void gemm_phase(PG8_LAS unsigned char* lds, const Gemm g, const Sched& S, const Epi& E) {
;     ...
;             PG8_LDA(At, 1, 1); PG8_STAGE(PG8_SB(1, 0), b3, voffB); PG8_STAGE(PG8_SB(1, 1), b3 + hstep, voffB); PG8_STAGE(PG8_SA(1, 0), a3, voffA);
;             PG8_WAIT_V(8); PG8_WAIT_L(0); PG8_BAR; PG8_MMA(1, 0, At, B0); PG8_MMA(1, 1, At, B1); PG8_BAR; PG8_SCHED;
	s_add_i32 s42, s59, s33
	v_lshl_add_u64 v[164:165], v[164:165], 0, s[12:13]
	s_mov_b32 m0, s42
	ds_read_b128 v[182:185], v171 offset:49152
	ds_read_b128 v[188:191], v171 offset:50176
	ds_read_b128 v[192:195], v171 offset:51200
	ds_read_b128 v[196:199], v171 offset:52224
	ds_read_b128 v[200:203], v171 offset:53248
	ds_read_b128 v[204:207], v171 offset:54272
	ds_read_b128 v[208:211], v171 offset:55296
	ds_read_b128 v[212:215], v171 offset:56320
	global_load_lds_dwordx4 v[164:165], off
	s_add_i32 m0, s42, 0x2000
	s_add_u32 s40, s40, 0x80080
	v_lshl_add_u64 v[164:165], v[216:217], 0, s[12:13]
	s_addc_u32 s41, s41, 0
	s_add_i32 s42, s60, s33
	global_load_lds_dwordx4 v[164:165], off
	v_lshl_add_u64 v[164:165], s[40:41], 0, v[144:145]
	s_mov_b32 m0, s42
	s_nop 0
	global_load_lds_dwordx4 v[164:165], off
	v_lshl_add_u64 v[164:165], s[40:41], 0, v[146:147]
	s_add_i32 m0, s42, 0x2000
	s_nop 0
	global_load_lds_dwordx4 v[164:165], off
	v_lshl_add_u64 v[164:165], v[218:219], 0, s[12:13]
	s_mov_b32 m0, s50
	s_nop 0
	global_load_lds_dwordx4 v[164:165], off
	v_lshl_add_u64 v[164:165], v[220:221], 0, s[12:13]
	s_mov_b32 m0, s51
	s_nop 0
	global_load_lds_dwordx4 v[164:165], off
	s_waitcnt vmcnt(8)
	s_waitcnt lgkmcnt(0)
	s_barrier
	s_setprio 1
	s_waitcnt lgkmcnt(0)
	v_mfma_f32_16x16x32_bf16 v[60:63], v[72:75], v[182:185], v[60:63]
	v_mfma_f32_16x16x32_bf16 v[56:59], v[92:95], v[182:185], v[56:59]
	v_mfma_f32_16x16x32_bf16 v[44:47], v[72:75], v[192:195], v[44:47]
	v_mfma_f32_16x16x32_bf16 v[40:43], v[92:95], v[192:195], v[40:43]
	v_mfma_f32_16x16x32_bf16 v[28:31], v[72:75], v[200:203], v[28:31]
	v_mfma_f32_16x16x32_bf16 v[24:27], v[92:95], v[200:203], v[24:27]
	v_mfma_f32_16x16x32_bf16 v[12:15], v[72:75], v[208:211], v[12:15]
	v_mfma_f32_16x16x32_bf16 v[8:11], v[92:95], v[208:211], v[8:11]
	v_mfma_f32_16x16x32_bf16 v[60:63], v[84:87], v[188:191], v[60:63]
	v_mfma_f32_16x16x32_bf16 v[56:59], v[96:99], v[188:191], v[56:59]
	v_mfma_f32_16x16x32_bf16 v[44:47], v[84:87], v[196:199], v[44:47]
	v_mfma_f32_16x16x32_bf16 v[40:43], v[96:99], v[196:199], v[40:43]
	v_mfma_f32_16x16x32_bf16 v[28:31], v[84:87], v[204:207], v[28:31]
	v_mfma_f32_16x16x32_bf16 v[24:27], v[96:99], v[204:207], v[24:27]
	v_mfma_f32_16x16x32_bf16 v[12:15], v[84:87], v[212:215], v[12:15]
	v_mfma_f32_16x16x32_bf16 v[8:11], v[96:99], v[212:215], v[8:11]
	s_setprio 0
	s_setprio 1
	v_mfma_f32_16x16x32_bf16 v[52:55], v[156:159], v[182:185], v[52:55]
	v_mfma_f32_16x16x32_bf16 v[48:51], v[174:177], v[182:185], v[48:51]
	v_mfma_f32_16x16x32_bf16 v[36:39], v[156:159], v[192:195], v[36:39]
	v_mfma_f32_16x16x32_bf16 v[32:35], v[174:177], v[192:195], v[32:35]
	v_mfma_f32_16x16x32_bf16 v[20:23], v[156:159], v[200:203], v[20:23]
	v_mfma_f32_16x16x32_bf16 v[16:19], v[174:177], v[200:203], v[16:19]
	v_mfma_f32_16x16x32_bf16 v[4:7], v[156:159], v[208:211], v[4:7]
	v_mfma_f32_16x16x32_bf16 v[0:3], v[174:177], v[208:211], v[0:3]
	v_mfma_f32_16x16x32_bf16 v[52:55], v[160:163], v[188:191], v[52:55]
	v_mfma_f32_16x16x32_bf16 v[48:51], v[178:181], v[188:191], v[48:51]
	v_mfma_f32_16x16x32_bf16 v[36:39], v[160:163], v[196:199], v[36:39]
	v_mfma_f32_16x16x32_bf16 v[32:35], v[178:181], v[196:199], v[32:35]
	v_mfma_f32_16x16x32_bf16 v[20:23], v[160:163], v[204:207], v[20:23]
	v_mfma_f32_16x16x32_bf16 v[16:19], v[178:181], v[204:207], v[16:19]
	v_mfma_f32_16x16x32_bf16 v[4:7], v[160:163], v[212:215], v[4:7]
	v_mfma_f32_16x16x32_bf16 v[0:3], v[178:181], v[212:215], v[0:3]
	s_setprio 0
	s_barrier
	s_add_i32 s58, s58, 2
	s_add_u32 s38, s38, 0x100
	s_addc_u32 s39, s39, 0
	s_add_u32 s56, s56, 0x100
	s_addc_u32 s57, s57, 0
	s_cmp_gt_u32 s58, 29

; #define PG8_STAGE(bufoff, gbase, voff) do { _Pragma("unroll") for (int _i = 0; _i < 2; ++_i) \
;         __builtin_amdgcn_global_load_lds((const unsigned*)((const char*)(gbase) + (voff)[_i]), (PG8_LAS unsigned*)(lds + (bufoff) + ldsw + _i * 8192), 16, 0, 0); } while (0)
; #define PG8_LDA(dst, b, h) do { _Pragma("unroll") for (int m = 0; m < 4; ++m) _Pragma("unroll") for (int k = 0; k < 2; ++k) dst[m][k] = *(const PG8_LAS bf16x8*)(lds + PG8_SA(b, h) + aoff + m * 2048 + k * 1024); } while (0)
; #define PG8_LDB(dst, b, h) do { _Pragma("unroll") for (int n = 0; n < 2; ++n) _Pragma("unroll") for (int k = 0; k < 2; ++k) dst[n][k] = *(const PG8_LAS bf16x8*)(lds + PG8_SB(b, h) + boff + n * 2048 + k * 1024); } while (0)
; #define PG8_MMA(ai, bj, At, Bt) do { __builtin_amdgcn_s_setprio(1); _Pragma("unroll") for (int m = 0; m < 4; ++m) _Pragma("unroll") for (int n = 0; n < 2; ++n) _Pragma("unroll") for (int k = 0; k < 2; ++k) \
;         acc[ai][bj][m][n] = __builtin_amdgcn_mfma_f32_16x16x32_bf16(Bt[n][k], At[m][k], acc[ai][bj][m][n], 0, 0, 0); __builtin_amdgcn_s_setprio(0); } while (0)
; #define PG8_WAIT_V(n) asm volatile("s_waitcnt vmcnt(" #n ")" ::: "memory")
; #define PG8_WAIT_L(n) asm volatile("s_waitcnt lgkmcnt(" #n ")" ::: "memory")
; #define PG8_BAR __builtin_amdgcn_s_barrier()
; #define PG8_SCHED __builtin_amdgcn_sched_barrier(0)
; template <class Epi, class Sched, bool ALIGN_EPI = false, bool SP2 = false>
; __device__ __forceinline__ void gemm_phase(PG8_LAS unsigned char* lds, const Gemm g, const Sched& S, const Epi& E) {
;     ...
;         for (int t = 0; t < nt; t += 2) {
;             const bool last = (t == nt - 2);
;             const char* a1 = cA + (size_t)(t + 1) * kstep;
;             const char* a2 = last ? nA : cA + (size_t)(t + 2) * kstep; const char* b2 = last ? nB : cB + (size_t)(t + 2) * kstep;
;             const char* a3 = a2 + kstep; const char* b3 = b2 + kstep;
;             if (last && has_next) S.a_ready(nxt);
;             if constexpr (SP2) {
;             PG8_LDB(B0, 0, 0); PG8_LDB(B1, 0, 1); PG8_SCHED; PG8_LDA(At, 0, 0); PG8_STAGE(PG8_SA(1, 1), a1 + hstep, voffA);
;             PG8_WAIT_V(8); PG8_WAIT_L(0); PG8_BAR; PG8_MMA(0, 0, At, B0); PG8_MMA(0, 1, At, B1); PG8_BAR; PG8_SCHED;
;             PG8_LDA(At, 0, 1); PG8_STAGE(PG8_SB(0, 0), b2, voffB); PG8_STAGE(PG8_SB(0, 1), b2 + hstep, voffB); PG8_STAGE(PG8_SA(0, 0), a2, voffA);
.LBB0_993:
	s_ashr_i32 s15, s14, 31
	s_lshl_b64 s[18:19], s[14:15], 20
	s_add_u32 s18, s8, s18
	s_addc_u32 s19, s9, s19
	s_and_b64 s[20:21], s[4:5], exec
	s_cselect_b32 s15, s19, s25
	s_cselect_b32 s43, s18, s24
	s_ashr_i32 s17, s16, 31
	s_lshl_b64 s[20:21], s[16:17], 20
	v_readlane_b32 s28, v236, 52
	v_readlane_b32 s29, v236, 53
	s_add_u32 s20, s28, s20
	s_addc_u32 s21, s29, s21
	s_and_b64 s[28:29], s[4:5], exec
	s_cselect_b32 s17, s21, s27
	s_cselect_b32 s44, s20, s26
	s_add_u32 s24, s24, 0x80080
	s_addc_u32 s25, s25, 0
	s_add_u32 s45, s26, 0x100
	s_addc_u32 s46, s27, 0
	s_mov_b32 s47, -2
	ds_read_b128 v[128:131], v173
	ds_read_b128 v[132:135], v173 offset:1024
	ds_read_b128 v[136:139], v173 offset:2048
	ds_read_b128 v[140:143], v173 offset:3072
	ds_read_b128 v[176:179], v174
	ds_read_b128 v[180:183], v174 offset:1024
	ds_read_b128 v[188:191], v174 offset:2048
	ds_read_b128 v[192:195], v174 offset:3072
	s_add_u32 s26, s24, 0xfff80080
	s_addc_u32 s27, s25, -1
	s_cmp_eq_u32 s47, 28
	s_cselect_b32 s29, s15, s27
	s_cselect_b32 s28, s43, s26
	s_cselect_b32 s27, s17, s46
	s_cselect_b32 s26, s44, s45
	v_lshl_add_u64 v[160:161], s[24:25], 0, v[152:153]
	s_add_i32 m0, s23, 0xc000
	ds_read_b128 v[196:199], v175
	ds_read_b128 v[200:203], v175 offset:1024
	ds_read_b128 v[204:207], v175 offset:2048
	ds_read_b128 v[208:211], v175 offset:3072
	ds_read_b128 v[212:215], v175 offset:4096
	ds_read_b128 v[216:219], v175 offset:5120
	ds_read_b128 v[220:223], v175 offset:6144
	ds_read_b128 v[224:227], v175 offset:7168
	global_load_lds_dwordx4 v[160:161], off
	v_lshl_add_u64 v[160:161], s[24:25], 0, v[154:155]
	s_add_i32 m0, s23, 0xe000
	s_nop 0
	global_load_lds_dwordx4 v[160:161], off
	s_waitcnt vmcnt(8)
	s_waitcnt lgkmcnt(0)
	s_barrier
	s_setprio 1
	s_waitcnt lgkmcnt(0)
	v_mfma_f32_16x16x32_bf16 v[124:127], v[128:131], v[196:199], 0
	v_mfma_f32_16x16x32_bf16 v[120:123], v[136:139], v[196:199], 0
	v_mfma_f32_16x16x32_bf16 v[108:111], v[128:131], v[204:207], 0
	v_mfma_f32_16x16x32_bf16 v[104:107], v[136:139], v[204:207], 0
	v_mfma_f32_16x16x32_bf16 v[92:95], v[128:131], v[212:215], 0
	v_mfma_f32_16x16x32_bf16 v[88:91], v[136:139], v[212:215], 0
	v_mfma_f32_16x16x32_bf16 v[76:79], v[128:131], v[220:223], 0
	v_mfma_f32_16x16x32_bf16 v[72:75], v[136:139], v[220:223], 0
	v_mfma_f32_16x16x32_bf16 v[124:127], v[132:135], v[200:203], v[124:127]
	v_mfma_f32_16x16x32_bf16 v[120:123], v[140:143], v[200:203], v[120:123]
	v_mfma_f32_16x16x32_bf16 v[108:111], v[132:135], v[208:211], v[108:111]
	v_mfma_f32_16x16x32_bf16 v[104:107], v[140:143], v[208:211], v[104:107]
	v_mfma_f32_16x16x32_bf16 v[92:95], v[132:135], v[216:219], v[92:95]
	v_mfma_f32_16x16x32_bf16 v[88:91], v[140:143], v[216:219], v[88:91]
	v_mfma_f32_16x16x32_bf16 v[76:79], v[132:135], v[224:227], v[76:79]
	v_mfma_f32_16x16x32_bf16 v[72:75], v[140:143], v[224:227], v[72:75]
	s_setprio 0
	s_setprio 1
	v_mfma_f32_16x16x32_bf16 v[116:119], v[176:179], v[196:199], 0
	v_mfma_f32_16x16x32_bf16 v[112:115], v[188:191], v[196:199], 0
	v_mfma_f32_16x16x32_bf16 v[100:103], v[176:179], v[204:207], 0
	v_mfma_f32_16x16x32_bf16 v[96:99], v[188:191], v[204:207], 0
	v_mfma_f32_16x16x32_bf16 v[84:87], v[176:179], v[212:215], 0
	v_mfma_f32_16x16x32_bf16 v[80:83], v[188:191], v[212:215], 0
	v_mfma_f32_16x16x32_bf16 v[68:71], v[176:179], v[220:223], 0
	v_mfma_f32_16x16x32_bf16 v[64:67], v[188:191], v[220:223], 0
	v_mfma_f32_16x16x32_bf16 v[116:119], v[180:183], v[200:203], v[116:119]
	v_mfma_f32_16x16x32_bf16 v[112:115], v[192:195], v[200:203], v[112:115]
	v_mfma_f32_16x16x32_bf16 v[100:103], v[180:183], v[208:211], v[100:103]
	v_mfma_f32_16x16x32_bf16 v[96:99], v[192:195], v[208:211], v[96:99]
	v_mfma_f32_16x16x32_bf16 v[84:87], v[180:183], v[216:219], v[84:87]
	v_mfma_f32_16x16x32_bf16 v[80:83], v[192:195], v[216:219], v[80:83]
	v_mfma_f32_16x16x32_bf16 v[68:71], v[180:183], v[224:227], v[68:71]
	v_mfma_f32_16x16x32_bf16 v[64:67], v[192:195], v[224:227], v[64:67]
	s_setprio 0
	s_barrier
	s_add_i32 s48, s40, s31
	v_lshl_add_u64 v[160:161], s[26:27], 0, v[146:147]
	s_mov_b32 m0, s48
	ds_read_b128 v[196:199], v175 offset:16384
	ds_read_b128 v[200:203], v175 offset:17408
	ds_read_b128 v[204:207], v175 offset:18432
	ds_read_b128 v[208:211], v175 offset:19456
	ds_read_b128 v[212:215], v175 offset:20480
	ds_read_b128 v[216:219], v175 offset:21504
	ds_read_b128 v[220:223], v175 offset:22528
	ds_read_b128 v[224:227], v175 offset:23552
	global_load_lds_dwordx4 v[160:161], off
	s_add_i32 m0, s48, 0x2000
	s_add_u32 s48, s26, 0x80000
	v_lshl_add_u64 v[184:185], s[26:27], 0, v[150:151]
	s_addc_u32 s49, s27, 0
	s_add_i32 s50, s41, s31
	global_load_lds_dwordx4 v[184:185], off
	v_lshl_add_u64 v[228:229], s[48:49], 0, v[146:147]
	s_mov_b32 m0, s50
	v_lshl_add_u64 v[230:231], s[28:29], 0, v[148:149]
	global_load_lds_dwordx4 v[228:229], off
	v_lshl_add_u64 v[228:229], s[48:49], 0, v[150:151]
	s_add_i32 m0, s50, 0x2000
	s_nop 0
	global_load_lds_dwordx4 v[228:229], off
	v_lshl_add_u64 v[228:229], s[28:29], 0, v[144:145]
	s_mov_b32 m0, s23
	s_nop 0
	global_load_lds_dwordx4 v[228:229], off
	s_mov_b32 m0, s33
	s_nop 0
	global_load_lds_dwordx4 v[230:231], off
	s_waitcnt vmcnt(8)
	s_waitcnt lgkmcnt(0)
	s_barrier
; #define PG8_STAGE(bufoff, gbase, voff) do { _Pragma("unroll") for (int _i = 0; _i < 2; ++_i) \
;         __builtin_amdgcn_global_load_lds((const unsigned*)((const char*)(gbase) + (voff)[_i]), (PG8_LAS unsigned*)(lds + (bufoff) + ldsw + _i * 8192), 16, 0, 0); } while (0)
; #define PG8_LDA(dst, b, h) do { _Pragma("unroll") for (int m = 0; m < 4; ++m) _Pragma("unroll") for (int k = 0; k < 2; ++k) dst[m][k] = *(const PG8_LAS bf16x8*)(lds + PG8_SA(b, h) + aoff + m * 2048 + k * 1024); } while (0)
; #define PG8_LDB(dst, b, h) do { _Pragma("unroll") for (int n = 0; n < 2; ++n) _Pragma("unroll") for (int k = 0; k < 2; ++k) dst[n][k] = *(const PG8_LAS bf16x8*)(lds + PG8_SB(b, h) + boff + n * 2048 + k * 1024); } while (0)
; #define PG8_MMA(ai, bj, At, Bt) do { __builtin_amdgcn_s_setprio(1); _Pragma("unroll") for (int m = 0; m < 4; ++m) _Pragma("unroll") for (int n = 0; n < 2; ++n) _Pragma("unroll") for (int k = 0; k < 2; ++k) \
;         acc[ai][bj][m][n] = __builtin_amdgcn_mfma_f32_16x16x32_bf16(Bt[n][k], At[m][k], acc[ai][bj][m][n], 0, 0, 0); __builtin_amdgcn_s_setprio(0); } while (0)
; #define PG8_WAIT_V(n) asm volatile("s_waitcnt vmcnt(" #n ")" ::: "memory")
; #define PG8_WAIT_L(n) asm volatile("s_waitcnt lgkmcnt(" #n ")" ::: "memory")
; #define PG8_BAR __builtin_amdgcn_s_barrier()
; #define PG8_SCHED __builtin_amdgcn_sched_barrier(0)
; template <class Epi, class Sched, bool ALIGN_EPI = false, bool SP2 = false>
; __device__ __forceinline__ void gemm_phase(PG8_LAS unsigned char* lds, const Gemm g, const Sched& S, const Epi& E) {
;     ...
;             PG8_LDA(At, 0, 1); PG8_STAGE(PG8_SB(0, 0), b2, voffB); PG8_STAGE(PG8_SB(0, 1), b2 + hstep, voffB); PG8_STAGE(PG8_SA(0, 0), a2, voffA);
;             PG8_WAIT_V(8); PG8_WAIT_L(0); PG8_BAR; PG8_MMA(1, 0, At, B0); PG8_MMA(1, 1, At, B1); PG8_BAR; PG8_SCHED;
;             PG8_LDB(B0, 1, 0); PG8_LDB(B1, 1, 1); PG8_SCHED; PG8_LDA(At, 1, 0); PG8_STAGE(PG8_SA(0, 1), a2 + hstep, voffA);
;             PG8_WAIT_V(8); PG8_WAIT_L(0); PG8_BAR; PG8_MMA(0, 0, At, B0); PG8_MMA(0, 1, At, B1); PG8_BAR; PG8_SCHED;
;             PG8_LDA(At, 1, 1); PG8_STAGE(PG8_SB(1, 0), b3, voffB); PG8_STAGE(PG8_SB(1, 1), b3 + hstep, voffB); PG8_STAGE(PG8_SA(1, 0), a3, voffA);
;             PG8_WAIT_V(8); PG8_WAIT_L(0); PG8_BAR; PG8_MMA(1, 0, At, B0); PG8_MMA(1, 1, At, B1); PG8_BAR; PG8_SCHED;
	s_setprio 1
	s_waitcnt lgkmcnt(0)
	v_mfma_f32_16x16x32_bf16 v[60:63], v[128:131], v[196:199], 0
	v_mfma_f32_16x16x32_bf16 v[56:59], v[136:139], v[196:199], 0
	v_mfma_f32_16x16x32_bf16 v[44:47], v[128:131], v[204:207], 0
	v_mfma_f32_16x16x32_bf16 v[40:43], v[136:139], v[204:207], 0
	v_mfma_f32_16x16x32_bf16 v[28:31], v[128:131], v[212:215], 0
	v_mfma_f32_16x16x32_bf16 v[24:27], v[136:139], v[212:215], 0
	v_mfma_f32_16x16x32_bf16 v[12:15], v[128:131], v[220:223], 0
	v_mfma_f32_16x16x32_bf16 v[8:11], v[136:139], v[220:223], 0
	v_mfma_f32_16x16x32_bf16 v[60:63], v[132:135], v[200:203], v[60:63]
	v_mfma_f32_16x16x32_bf16 v[56:59], v[140:143], v[200:203], v[56:59]
	v_mfma_f32_16x16x32_bf16 v[44:47], v[132:135], v[208:211], v[44:47]
	v_mfma_f32_16x16x32_bf16 v[40:43], v[140:143], v[208:211], v[40:43]
	v_mfma_f32_16x16x32_bf16 v[28:31], v[132:135], v[216:219], v[28:31]
	v_mfma_f32_16x16x32_bf16 v[24:27], v[140:143], v[216:219], v[24:27]
	v_mfma_f32_16x16x32_bf16 v[12:15], v[132:135], v[224:227], v[12:15]
	v_mfma_f32_16x16x32_bf16 v[8:11], v[140:143], v[224:227], v[8:11]
	s_setprio 0
	s_setprio 1
	v_mfma_f32_16x16x32_bf16 v[52:55], v[176:179], v[196:199], 0
	v_mfma_f32_16x16x32_bf16 v[48:51], v[188:191], v[196:199], 0
	v_mfma_f32_16x16x32_bf16 v[36:39], v[176:179], v[204:207], 0
	v_mfma_f32_16x16x32_bf16 v[32:35], v[188:191], v[204:207], 0
	v_mfma_f32_16x16x32_bf16 v[20:23], v[176:179], v[212:215], 0
	v_mfma_f32_16x16x32_bf16 v[16:19], v[188:191], v[212:215], 0
	v_mfma_f32_16x16x32_bf16 v[4:7], v[176:179], v[220:223], 0
	v_mfma_f32_16x16x32_bf16 v[0:3], v[188:191], v[220:223], 0
	v_mfma_f32_16x16x32_bf16 v[52:55], v[180:183], v[200:203], v[52:55]
	v_mfma_f32_16x16x32_bf16 v[48:51], v[192:195], v[200:203], v[48:51]
	v_mfma_f32_16x16x32_bf16 v[36:39], v[180:183], v[208:211], v[36:39]
	v_mfma_f32_16x16x32_bf16 v[32:35], v[192:195], v[208:211], v[32:35]
	v_mfma_f32_16x16x32_bf16 v[20:23], v[180:183], v[216:219], v[20:23]
	v_mfma_f32_16x16x32_bf16 v[16:19], v[192:195], v[216:219], v[16:19]
	v_mfma_f32_16x16x32_bf16 v[4:7], v[180:183], v[224:227], v[4:7]
	v_mfma_f32_16x16x32_bf16 v[0:3], v[192:195], v[224:227], v[0:3]
	s_setprio 0
	s_barrier
	s_add_i32 s48, 0, 0x18000
	s_add_i32 s49, 0, 0x1c000
	v_add_u32_e32 v140, s48, v163
	v_add_u32_e32 v187, s49, v163
	ds_read_b128 v[128:131], v140
	ds_read_b128 v[132:135], v140 offset:1024
	ds_read_b128 v[136:139], v140 offset:2048
	ds_read_b128 v[140:143], v140 offset:3072
	ds_read_b128 v[176:179], v187
	ds_read_b128 v[180:183], v187 offset:1024
	ds_read_b128 v[188:191], v187 offset:2048
	ds_read_b128 v[192:195], v187 offset:3072
	s_add_u32 s28, s28, 0x80000
	s_addc_u32 s29, s29, 0
	s_mov_b32 m0, s34
	v_lshl_add_u64 v[232:233], s[28:29], 0, v[144:145]
	ds_read_b128 v[196:199], v175 offset:32768
	ds_read_b128 v[200:203], v175 offset:33792
	ds_read_b128 v[204:207], v175 offset:34816
	ds_read_b128 v[208:211], v175 offset:35840
	ds_read_b128 v[212:215], v175 offset:36864
	ds_read_b128 v[216:219], v175 offset:37888
	ds_read_b128 v[220:223], v175 offset:38912
	ds_read_b128 v[224:227], v175 offset:39936
	global_load_lds_dwordx4 v[232:233], off
	v_lshl_add_u64 v[232:233], s[28:29], 0, v[148:149]
	s_mov_b32 m0, s35
	s_nop 0
	global_load_lds_dwordx4 v[232:233], off
	s_waitcnt vmcnt(8)
	s_waitcnt lgkmcnt(0)
	s_barrier
	s_setprio 1
	s_waitcnt lgkmcnt(0)
	v_mfma_f32_16x16x32_bf16 v[124:127], v[128:131], v[196:199], v[124:127]
	v_mfma_f32_16x16x32_bf16 v[120:123], v[136:139], v[196:199], v[120:123]
	v_mfma_f32_16x16x32_bf16 v[108:111], v[128:131], v[204:207], v[108:111]
	v_mfma_f32_16x16x32_bf16 v[104:107], v[136:139], v[204:207], v[104:107]
	v_mfma_f32_16x16x32_bf16 v[92:95], v[128:131], v[212:215], v[92:95]
	v_mfma_f32_16x16x32_bf16 v[88:91], v[136:139], v[212:215], v[88:91]
	v_mfma_f32_16x16x32_bf16 v[76:79], v[128:131], v[220:223], v[76:79]
	v_mfma_f32_16x16x32_bf16 v[72:75], v[136:139], v[220:223], v[72:75]
	v_mfma_f32_16x16x32_bf16 v[124:127], v[132:135], v[200:203], v[124:127]
	v_mfma_f32_16x16x32_bf16 v[120:123], v[140:143], v[200:203], v[120:123]
	v_mfma_f32_16x16x32_bf16 v[108:111], v[132:135], v[208:211], v[108:111]
	v_mfma_f32_16x16x32_bf16 v[104:107], v[140:143], v[208:211], v[104:107]
	v_mfma_f32_16x16x32_bf16 v[92:95], v[132:135], v[216:219], v[92:95]
	v_mfma_f32_16x16x32_bf16 v[88:91], v[140:143], v[216:219], v[88:91]
	v_mfma_f32_16x16x32_bf16 v[76:79], v[132:135], v[224:227], v[76:79]
	v_mfma_f32_16x16x32_bf16 v[72:75], v[140:143], v[224:227], v[72:75]
	s_setprio 0
	s_setprio 1
	v_mfma_f32_16x16x32_bf16 v[116:119], v[176:179], v[196:199], v[116:119]
	v_mfma_f32_16x16x32_bf16 v[112:115], v[188:191], v[196:199], v[112:115]
	v_mfma_f32_16x16x32_bf16 v[100:103], v[176:179], v[204:207], v[100:103]
	v_mfma_f32_16x16x32_bf16 v[96:99], v[188:191], v[204:207], v[96:99]
	v_mfma_f32_16x16x32_bf16 v[84:87], v[176:179], v[212:215], v[84:87]
	v_mfma_f32_16x16x32_bf16 v[80:83], v[188:191], v[212:215], v[80:83]
	v_mfma_f32_16x16x32_bf16 v[68:71], v[176:179], v[220:223], v[68:71]
	v_mfma_f32_16x16x32_bf16 v[64:67], v[188:191], v[220:223], v[64:67]
	v_mfma_f32_16x16x32_bf16 v[116:119], v[180:183], v[200:203], v[116:119]
	v_mfma_f32_16x16x32_bf16 v[112:115], v[192:195], v[200:203], v[112:115]
	v_mfma_f32_16x16x32_bf16 v[100:103], v[180:183], v[208:211], v[100:103]
	v_mfma_f32_16x16x32_bf16 v[96:99], v[192:195], v[208:211], v[96:99]
	v_mfma_f32_16x16x32_bf16 v[84:87], v[180:183], v[216:219], v[84:87]
	v_mfma_f32_16x16x32_bf16 v[80:83], v[192:195], v[216:219], v[80:83]
	v_mfma_f32_16x16x32_bf16 v[68:71], v[180:183], v[224:227], v[68:71]
	v_mfma_f32_16x16x32_bf16 v[64:67], v[192:195], v[224:227], v[64:67]
	s_setprio 0
	s_barrier
; #define PG8_STAGE(bufoff, gbase, voff) do { _Pragma("unroll") for (int _i = 0; _i < 2; ++_i) \
;         __builtin_amdgcn_global_load_lds((const unsigned*)((const char*)(gbase) + (voff)[_i]), (PG8_LAS unsigned*)(lds + (bufoff) + ldsw + _i * 8192), 16, 0, 0); } while (0)
; #define PG8_LDA(dst, b, h) do { _Pragma("unroll") for (int m = 0; m < 4; ++m) _Pragma("unroll") for (int k = 0; k < 2; ++k) dst[m][k] = *(const PG8_LAS bf16x8*)(lds + PG8_SA(b, h) + aoff + m * 2048 + k * 1024); } while (0)
; #define PG8_MMA(ai, bj, At, Bt) do { __builtin_amdgcn_s_setprio(1); _Pragma("unroll") for (int m = 0; m < 4; ++m) _Pragma("unroll") for (int n = 0; n < 2; ++n) _Pragma("unroll") for (int k = 0; k < 2; ++k) \
;         acc[ai][bj][m][n] = __builtin_amdgcn_mfma_f32_16x16x32_bf16(Bt[n][k], At[m][k], acc[ai][bj][m][n], 0, 0, 0); __builtin_amdgcn_s_setprio(0); } while (0)
; #define PG8_WAIT_V(n) asm volatile("s_waitcnt vmcnt(" #n ")" ::: "memory")
; #define PG8_WAIT_L(n) asm volatile("s_waitcnt lgkmcnt(" #n ")" ::: "memory")
; #define PG8_BAR __builtin_amdgcn_s_barrier()
; #define PG8_SCHED __builtin_amdgcn_sched_barrier(0)
; template <class Epi, class Sched, bool ALIGN_EPI = false, bool SP2 = false>
; __device__ __forceinline__ void gemm_phase(PG8_LAS unsigned char* lds, const Gemm g, const Sched& S, const Epi& E) {
;     ...
;         for (int t = 0; t < nt; t += 2) {
;             const bool last = (t == nt - 2);
;             const char* a1 = cA + (size_t)(t + 1) * kstep;
;             const char* a2 = last ? nA : cA + (size_t)(t + 2) * kstep; const char* b2 = last ? nB : cB + (size_t)(t + 2) * kstep;
;     ...
;             PG8_LDA(At, 1, 1); PG8_STAGE(PG8_SB(1, 0), b3, voffB); PG8_STAGE(PG8_SB(1, 1), b3 + hstep, voffB); PG8_STAGE(PG8_SA(1, 0), a3, voffA);
;             PG8_WAIT_V(8); PG8_WAIT_L(0); PG8_BAR; PG8_MMA(1, 0, At, B0); PG8_MMA(1, 1, At, B1); PG8_BAR; PG8_SCHED;
	s_add_i32 s28, s48, s31
	v_lshl_add_u64 v[160:161], v[160:161], 0, s[10:11]
	s_mov_b32 m0, s28
	ds_read_b128 v[196:199], v175 offset:49152
	ds_read_b128 v[200:203], v175 offset:50176
	ds_read_b128 v[204:207], v175 offset:51200
	ds_read_b128 v[208:211], v175 offset:52224
	ds_read_b128 v[212:215], v175 offset:53248
	ds_read_b128 v[216:219], v175 offset:54272
	ds_read_b128 v[220:223], v175 offset:55296
	ds_read_b128 v[224:227], v175 offset:56320
	global_load_lds_dwordx4 v[160:161], off
	s_add_i32 m0, s28, 0x2000
	s_add_u32 s26, s26, 0x80080
	v_lshl_add_u64 v[160:161], v[184:185], 0, s[10:11]
	s_addc_u32 s27, s27, 0
	s_add_i32 s28, s49, s31
	global_load_lds_dwordx4 v[160:161], off
	v_lshl_add_u64 v[160:161], s[26:27], 0, v[146:147]
	s_mov_b32 m0, s28
	s_nop 0
	global_load_lds_dwordx4 v[160:161], off
	v_lshl_add_u64 v[160:161], s[26:27], 0, v[150:151]
	s_add_i32 m0, s28, 0x2000
	s_nop 0
	global_load_lds_dwordx4 v[160:161], off
	v_lshl_add_u64 v[160:161], v[228:229], 0, s[10:11]
	s_mov_b32 m0, s38
	s_nop 0
	global_load_lds_dwordx4 v[160:161], off
	v_lshl_add_u64 v[160:161], v[230:231], 0, s[10:11]
	s_mov_b32 m0, s39
	s_nop 0
	global_load_lds_dwordx4 v[160:161], off
	s_waitcnt vmcnt(8)
	s_waitcnt lgkmcnt(0)
	s_barrier
	s_setprio 1
	s_waitcnt lgkmcnt(0)
	v_mfma_f32_16x16x32_bf16 v[60:63], v[128:131], v[196:199], v[60:63]
	v_mfma_f32_16x16x32_bf16 v[56:59], v[136:139], v[196:199], v[56:59]
	v_mfma_f32_16x16x32_bf16 v[44:47], v[128:131], v[204:207], v[44:47]
	v_mfma_f32_16x16x32_bf16 v[40:43], v[136:139], v[204:207], v[40:43]
	v_mfma_f32_16x16x32_bf16 v[28:31], v[128:131], v[212:215], v[28:31]
	v_mfma_f32_16x16x32_bf16 v[24:27], v[136:139], v[212:215], v[24:27]
	v_mfma_f32_16x16x32_bf16 v[12:15], v[128:131], v[220:223], v[12:15]
	v_mfma_f32_16x16x32_bf16 v[8:11], v[136:139], v[220:223], v[8:11]
	v_mfma_f32_16x16x32_bf16 v[60:63], v[132:135], v[200:203], v[60:63]
	v_mfma_f32_16x16x32_bf16 v[56:59], v[140:143], v[200:203], v[56:59]
	v_mfma_f32_16x16x32_bf16 v[44:47], v[132:135], v[208:211], v[44:47]
	v_mfma_f32_16x16x32_bf16 v[40:43], v[140:143], v[208:211], v[40:43]
	v_mfma_f32_16x16x32_bf16 v[28:31], v[132:135], v[216:219], v[28:31]
	v_mfma_f32_16x16x32_bf16 v[24:27], v[140:143], v[216:219], v[24:27]
	v_mfma_f32_16x16x32_bf16 v[12:15], v[132:135], v[224:227], v[12:15]
	v_mfma_f32_16x16x32_bf16 v[8:11], v[140:143], v[224:227], v[8:11]
	s_setprio 0
	s_setprio 1
	v_mfma_f32_16x16x32_bf16 v[52:55], v[176:179], v[196:199], v[52:55]
	v_mfma_f32_16x16x32_bf16 v[48:51], v[188:191], v[196:199], v[48:51]
	v_mfma_f32_16x16x32_bf16 v[36:39], v[176:179], v[204:207], v[36:39]
	v_mfma_f32_16x16x32_bf16 v[32:35], v[188:191], v[204:207], v[32:35]
	v_mfma_f32_16x16x32_bf16 v[20:23], v[176:179], v[212:215], v[20:23]
	v_mfma_f32_16x16x32_bf16 v[16:19], v[188:191], v[212:215], v[16:19]
	v_mfma_f32_16x16x32_bf16 v[4:7], v[176:179], v[220:223], v[4:7]
	v_mfma_f32_16x16x32_bf16 v[0:3], v[188:191], v[220:223], v[0:3]
	v_mfma_f32_16x16x32_bf16 v[52:55], v[180:183], v[200:203], v[52:55]
	v_mfma_f32_16x16x32_bf16 v[48:51], v[192:195], v[200:203], v[48:51]
	v_mfma_f32_16x16x32_bf16 v[36:39], v[180:183], v[208:211], v[36:39]
	v_mfma_f32_16x16x32_bf16 v[32:35], v[192:195], v[208:211], v[32:35]
	v_mfma_f32_16x16x32_bf16 v[20:23], v[180:183], v[216:219], v[20:23]
	v_mfma_f32_16x16x32_bf16 v[16:19], v[192:195], v[216:219], v[16:19]
	v_mfma_f32_16x16x32_bf16 v[4:7], v[180:183], v[224:227], v[4:7]
	v_mfma_f32_16x16x32_bf16 v[0:3], v[192:195], v[224:227], v[0:3]
	s_setprio 0
	s_barrier
	s_add_i32 s47, s47, 2
	s_add_u32 s24, s24, 0x100
	s_addc_u32 s25, s25, 0
	s_add_u32 s45, s45, 0x100
	s_addc_u32 s46, s46, 0
	s_cmp_gt_u32 s47, 29

; #define PG8_STAGE(bufoff, gbase, voff) do { _Pragma("unroll") for (int _i = 0; _i < 2; ++_i) \
;         __builtin_amdgcn_global_load_lds((const unsigned*)((const char*)(gbase) + (voff)[_i]), (PG8_LAS unsigned*)(lds + (bufoff) + ldsw + _i * 8192), 16, 0, 0); } while (0)
; #define PG8_LDA(dst, b, h) do { _Pragma("unroll") for (int m = 0; m < 4; ++m) _Pragma("unroll") for (int k = 0; k < 2; ++k) dst[m][k] = *(const PG8_LAS bf16x8*)(lds + PG8_SA(b, h) + aoff + m * 2048 + k * 1024); } while (0)
; #define PG8_LDB(dst, b, h) do { _Pragma("unroll") for (int n = 0; n < 2; ++n) _Pragma("unroll") for (int k = 0; k < 2; ++k) dst[n][k] = *(const PG8_LAS bf16x8*)(lds + PG8_SB(b, h) + boff + n * 2048 + k * 1024); } while (0)
; #define PG8_MMA(ai, bj, At, Bt) do { __builtin_amdgcn_s_setprio(1); _Pragma("unroll") for (int m = 0; m < 4; ++m) _Pragma("unroll") for (int n = 0; n < 2; ++n) _Pragma("unroll") for (int k = 0; k < 2; ++k) \
;         acc[ai][bj][m][n] = __builtin_amdgcn_mfma_f32_16x16x32_bf16(Bt[n][k], At[m][k], acc[ai][bj][m][n], 0, 0, 0); __builtin_amdgcn_s_setprio(0); } while (0)
; #define PG8_WAIT_V(n) asm volatile("s_waitcnt vmcnt(" #n ")" ::: "memory")
; #define PG8_BAR __builtin_amdgcn_s_barrier()
; template <class Epi, class Sched, bool ALIGN_EPI = false, bool SP2 = false>
; __device__ __forceinline__ void gemm_phase(PG8_LAS unsigned char* lds, const Gemm g, const Sched& S, const Epi& E) {
;     ...
;             const char* a2 = last ? nA : cA + (size_t)(t + 2) * kstep; const char* b2 = last ? nB : cB + (size_t)(t + 2) * kstep;
;             const char* a3 = a2 + kstep; const char* b3 = b2 + kstep;
;             if (last && has_next) S.a_ready(nxt);
;             if constexpr (SP2) {
;             PG8_LDB(B0, 0, 0); PG8_LDB(B1, 0, 1); PG8_SCHED; PG8_LDA(At, 0, 0); PG8_STAGE(PG8_SA(1, 1), a1 + hstep, voffA);
;             PG8_WAIT_V(8); PG8_WAIT_L(0); PG8_BAR; PG8_MMA(0, 0, At, B0); PG8_MMA(0, 1, At, B1); PG8_BAR; PG8_SCHED;
;             PG8_LDA(At, 0, 1); PG8_STAGE(PG8_SB(0, 0), b2, voffB); PG8_STAGE(PG8_SB(0, 1), b2 + hstep, voffB); PG8_STAGE(PG8_SA(0, 0), a2, voffA);
;     ...
;         for (int a = 0; a < 2; ++a)
; #pragma unroll
;             for (int b = 0; b < 2; ++b)
; #pragma unroll
;                 for (int m = 0; m < 4; ++m)
; #pragma unroll
;                     for (int n = 0; n < 2; ++n) acc[a][b][m][n] = (f32x4){0.f, 0.f, 0.f, 0.f};
.LBB0_1070:
	s_ashr_i32 s19, s18, 31
	s_lshl_b64 s[20:21], s[18:19], 22
	s_add_u32 s20, s72, s20
	s_addc_u32 s21, s73, s21
	s_and_b64 s[22:23], s[0:1], exec
	s_cselect_b32 s19, s21, s27
	s_cselect_b32 s51, s20, s26
	s_ashr_i32 s17, s16, 31
	s_lshl_b64 s[22:23], s[16:17], 22
	v_readlane_b32 s30, v236, 54
	v_readlane_b32 s31, v236, 55
	s_add_u32 s22, s30, s22
	s_addc_u32 s23, s31, s23
	s_and_b64 s[30:31], s[0:1], exec
	s_cselect_b32 s17, s23, s29
	s_cselect_b32 s52, s22, s28
	s_add_u32 s26, s26, 0x200080
	s_addc_u32 s27, s27, 0
	s_add_u32 s53, s28, 0x100
	s_addc_u32 s54, s29, 0
	s_mov_b32 s55, -2
	ds_read_b128 v[64:67], v165
	ds_read_b128 v[108:111], v165 offset:1024
	ds_read_b128 v[116:119], v165 offset:2048
	ds_read_b128 v[128:131], v165 offset:3072
	ds_read_b128 v[156:159], v166
	ds_read_b128 v[168:171], v166 offset:1024
	ds_read_b128 v[172:175], v166 offset:2048
	ds_read_b128 v[176:179], v166 offset:3072
	s_add_u32 s28, s26, 0xffe00080
	s_addc_u32 s29, s27, -1
	s_cmpk_eq_i32 s55, 0x7c
	s_cselect_b32 s31, s19, s29
	s_cselect_b32 s30, s51, s28
	s_cselect_b32 s29, s17, s54
	s_cselect_b32 s28, s52, s53
	v_lshl_add_u64 v[160:161], s[26:27], 0, v[148:149]
	s_add_i32 m0, s35, 0xc000
	ds_read_b128 v[180:183], v167
	ds_read_b128 v[184:187], v167 offset:1024
	ds_read_b128 v[188:191], v167 offset:2048
	ds_read_b128 v[192:195], v167 offset:3072
	ds_read_b128 v[196:199], v167 offset:4096
	ds_read_b128 v[200:203], v167 offset:5120
	ds_read_b128 v[204:207], v167 offset:6144
	ds_read_b128 v[208:211], v167 offset:7168
	global_load_lds_dwordx4 v[160:161], off
	v_lshl_add_u64 v[160:161], s[26:27], 0, v[150:151]
	s_add_i32 m0, s35, 0xe000
	s_nop 0
	global_load_lds_dwordx4 v[160:161], off
	s_waitcnt vmcnt(8)
	s_waitcnt lgkmcnt(0)
	s_barrier
	s_setprio 1
	s_waitcnt lgkmcnt(0)
	v_mfma_f32_16x16x32_bf16 v[140:143], v[64:67], v[180:183], 0
	v_mfma_f32_16x16x32_bf16 v[136:139], v[116:119], v[180:183], 0
	v_mfma_f32_16x16x32_bf16 v[120:123], v[64:67], v[188:191], 0
	v_mfma_f32_16x16x32_bf16 v[112:115], v[116:119], v[188:191], 0
	v_mfma_f32_16x16x32_bf16 v[96:99], v[64:67], v[196:199], 0
	v_mfma_f32_16x16x32_bf16 v[92:95], v[116:119], v[196:199], 0
	v_mfma_f32_16x16x32_bf16 v[80:83], v[64:67], v[204:207], 0
	v_mfma_f32_16x16x32_bf16 v[76:79], v[116:119], v[204:207], 0
	v_mfma_f32_16x16x32_bf16 v[140:143], v[108:111], v[184:187], v[140:143]
	v_mfma_f32_16x16x32_bf16 v[136:139], v[128:131], v[184:187], v[136:139]
	v_mfma_f32_16x16x32_bf16 v[120:123], v[108:111], v[192:195], v[120:123]
	v_mfma_f32_16x16x32_bf16 v[112:115], v[128:131], v[192:195], v[112:115]
	v_mfma_f32_16x16x32_bf16 v[96:99], v[108:111], v[200:203], v[96:99]
	v_mfma_f32_16x16x32_bf16 v[92:95], v[128:131], v[200:203], v[92:95]
	v_mfma_f32_16x16x32_bf16 v[80:83], v[108:111], v[208:211], v[80:83]
	v_mfma_f32_16x16x32_bf16 v[76:79], v[128:131], v[208:211], v[76:79]
	s_setprio 0
	s_setprio 1
	v_mfma_f32_16x16x32_bf16 v[132:135], v[156:159], v[180:183], 0
	v_mfma_f32_16x16x32_bf16 v[124:127], v[172:175], v[180:183], 0
	v_mfma_f32_16x16x32_bf16 v[104:107], v[156:159], v[188:191], 0
	v_mfma_f32_16x16x32_bf16 v[100:103], v[172:175], v[188:191], 0
	v_mfma_f32_16x16x32_bf16 v[88:91], v[156:159], v[196:199], 0
	v_mfma_f32_16x16x32_bf16 v[84:87], v[172:175], v[196:199], 0
	v_mfma_f32_16x16x32_bf16 v[72:75], v[156:159], v[204:207], 0
	v_mfma_f32_16x16x32_bf16 v[68:71], v[172:175], v[204:207], 0
	v_mfma_f32_16x16x32_bf16 v[132:135], v[168:171], v[184:187], v[132:135]
	v_mfma_f32_16x16x32_bf16 v[124:127], v[176:179], v[184:187], v[124:127]
	v_mfma_f32_16x16x32_bf16 v[104:107], v[168:171], v[192:195], v[104:107]
	v_mfma_f32_16x16x32_bf16 v[100:103], v[176:179], v[192:195], v[100:103]
	v_mfma_f32_16x16x32_bf16 v[88:91], v[168:171], v[200:203], v[88:91]
	v_mfma_f32_16x16x32_bf16 v[84:87], v[176:179], v[200:203], v[84:87]
	v_mfma_f32_16x16x32_bf16 v[72:75], v[168:171], v[208:211], v[72:75]
	v_mfma_f32_16x16x32_bf16 v[68:71], v[176:179], v[208:211], v[68:71]
	s_setprio 0
	s_barrier
	s_add_i32 s56, s45, s34
	v_lshl_add_u64 v[160:161], s[28:29], 0, v[144:145]
	s_mov_b32 m0, s56
	ds_read_b128 v[180:183], v167 offset:16384
	ds_read_b128 v[184:187], v167 offset:17408
	ds_read_b128 v[188:191], v167 offset:18432
	ds_read_b128 v[192:195], v167 offset:19456
	ds_read_b128 v[196:199], v167 offset:20480
	ds_read_b128 v[200:203], v167 offset:21504
	ds_read_b128 v[204:207], v167 offset:22528
	ds_read_b128 v[208:211], v167 offset:23552
	global_load_lds_dwordx4 v[160:161], off
	s_add_i32 m0, s56, 0x2000
	s_add_u32 s56, s28, 0x200000
	v_lshl_add_u64 v[212:213], s[28:29], 0, v[146:147]
	s_addc_u32 s57, s29, 0
	s_add_i32 s58, s46, s34
	global_load_lds_dwordx4 v[212:213], off
	v_lshl_add_u64 v[214:215], s[56:57], 0, v[144:145]
	s_mov_b32 m0, s58
	v_lshl_add_u64 v[216:217], s[30:31], 0, v[146:147]
	global_load_lds_dwordx4 v[214:215], off
	v_lshl_add_u64 v[214:215], s[56:57], 0, v[146:147]
	s_add_i32 m0, s58, 0x2000
	s_nop 0
	global_load_lds_dwordx4 v[214:215], off
	v_lshl_add_u64 v[214:215], s[30:31], 0, v[144:145]
	s_mov_b32 m0, s35
	s_nop 0
	global_load_lds_dwordx4 v[214:215], off
	s_mov_b32 m0, s36
	s_nop 0
	global_load_lds_dwordx4 v[216:217], off
	s_waitcnt vmcnt(8)
	s_waitcnt lgkmcnt(0)
	s_barrier
; #define PG8_STAGE(bufoff, gbase, voff) do { _Pragma("unroll") for (int _i = 0; _i < 2; ++_i) \
;         __builtin_amdgcn_global_load_lds((const unsigned*)((const char*)(gbase) + (voff)[_i]), (PG8_LAS unsigned*)(lds + (bufoff) + ldsw + _i * 8192), 16, 0, 0); } while (0)
; #define PG8_LDA(dst, b, h) do { _Pragma("unroll") for (int m = 0; m < 4; ++m) _Pragma("unroll") for (int k = 0; k < 2; ++k) dst[m][k] = *(const PG8_LAS bf16x8*)(lds + PG8_SA(b, h) + aoff + m * 2048 + k * 1024); } while (0)
; #define PG8_LDB(dst, b, h) do { _Pragma("unroll") for (int n = 0; n < 2; ++n) _Pragma("unroll") for (int k = 0; k < 2; ++k) dst[n][k] = *(const PG8_LAS bf16x8*)(lds + PG8_SB(b, h) + boff + n * 2048 + k * 1024); } while (0)
; #define PG8_MMA(ai, bj, At, Bt) do { __builtin_amdgcn_s_setprio(1); _Pragma("unroll") for (int m = 0; m < 4; ++m) _Pragma("unroll") for (int n = 0; n < 2; ++n) _Pragma("unroll") for (int k = 0; k < 2; ++k) \
;         acc[ai][bj][m][n] = __builtin_amdgcn_mfma_f32_16x16x32_bf16(Bt[n][k], At[m][k], acc[ai][bj][m][n], 0, 0, 0); __builtin_amdgcn_s_setprio(0); } while (0)
; #define PG8_WAIT_V(n) asm volatile("s_waitcnt vmcnt(" #n ")" ::: "memory")
; #define PG8_WAIT_L(n) asm volatile("s_waitcnt lgkmcnt(" #n ")" ::: "memory")
; #define PG8_BAR __builtin_amdgcn_s_barrier()
; #define PG8_SCHED __builtin_amdgcn_sched_barrier(0)
; template <class Epi, class Sched, bool ALIGN_EPI = false, bool SP2 = false>
; __device__ __forceinline__ void gemm_phase(PG8_LAS unsigned char* lds, const Gemm g, const Sched& S, const Epi& E) {
;     ...
;             PG8_WAIT_V(8); PG8_WAIT_L(0); PG8_BAR; PG8_MMA(1, 0, At, B0); PG8_MMA(1, 1, At, B1); PG8_BAR; PG8_SCHED;
;             PG8_LDB(B0, 1, 0); PG8_LDB(B1, 1, 1); PG8_SCHED; PG8_LDA(At, 1, 0); PG8_STAGE(PG8_SA(0, 1), a2 + hstep, voffA);
;             PG8_WAIT_V(8); PG8_WAIT_L(0); PG8_BAR; PG8_MMA(0, 0, At, B0); PG8_MMA(0, 1, At, B1); PG8_BAR; PG8_SCHED;
	s_setprio 1
	s_waitcnt lgkmcnt(0)
	v_mfma_f32_16x16x32_bf16 v[60:63], v[64:67], v[180:183], 0
	v_mfma_f32_16x16x32_bf16 v[56:59], v[116:119], v[180:183], 0
	v_mfma_f32_16x16x32_bf16 v[44:47], v[64:67], v[188:191], 0
	v_mfma_f32_16x16x32_bf16 v[40:43], v[116:119], v[188:191], 0
	v_mfma_f32_16x16x32_bf16 v[28:31], v[64:67], v[196:199], 0
	v_mfma_f32_16x16x32_bf16 v[24:27], v[116:119], v[196:199], 0
	v_mfma_f32_16x16x32_bf16 v[12:15], v[64:67], v[204:207], 0
	v_mfma_f32_16x16x32_bf16 v[8:11], v[116:119], v[204:207], 0
	v_mfma_f32_16x16x32_bf16 v[60:63], v[108:111], v[184:187], v[60:63]
	v_mfma_f32_16x16x32_bf16 v[56:59], v[128:131], v[184:187], v[56:59]
	v_mfma_f32_16x16x32_bf16 v[44:47], v[108:111], v[192:195], v[44:47]
	v_mfma_f32_16x16x32_bf16 v[40:43], v[128:131], v[192:195], v[40:43]
	v_mfma_f32_16x16x32_bf16 v[28:31], v[108:111], v[200:203], v[28:31]
	v_mfma_f32_16x16x32_bf16 v[24:27], v[128:131], v[200:203], v[24:27]
	v_mfma_f32_16x16x32_bf16 v[12:15], v[108:111], v[208:211], v[12:15]
	v_mfma_f32_16x16x32_bf16 v[8:11], v[128:131], v[208:211], v[8:11]
	s_setprio 0
	s_setprio 1
	v_mfma_f32_16x16x32_bf16 v[52:55], v[156:159], v[180:183], 0
	v_mfma_f32_16x16x32_bf16 v[48:51], v[172:175], v[180:183], 0
	v_mfma_f32_16x16x32_bf16 v[36:39], v[156:159], v[188:191], 0
	v_mfma_f32_16x16x32_bf16 v[32:35], v[172:175], v[188:191], 0
	v_mfma_f32_16x16x32_bf16 v[20:23], v[156:159], v[196:199], 0
	v_mfma_f32_16x16x32_bf16 v[16:19], v[172:175], v[196:199], 0
	v_mfma_f32_16x16x32_bf16 v[4:7], v[156:159], v[204:207], 0
	v_mfma_f32_16x16x32_bf16 v[0:3], v[172:175], v[204:207], 0
	v_mfma_f32_16x16x32_bf16 v[52:55], v[168:171], v[184:187], v[52:55]
	v_mfma_f32_16x16x32_bf16 v[48:51], v[176:179], v[184:187], v[48:51]
	v_mfma_f32_16x16x32_bf16 v[36:39], v[168:171], v[192:195], v[36:39]
	v_mfma_f32_16x16x32_bf16 v[32:35], v[176:179], v[192:195], v[32:35]
	v_mfma_f32_16x16x32_bf16 v[20:23], v[168:171], v[200:203], v[20:23]
	v_mfma_f32_16x16x32_bf16 v[16:19], v[176:179], v[200:203], v[16:19]
	v_mfma_f32_16x16x32_bf16 v[4:7], v[168:171], v[208:211], v[4:7]
	v_mfma_f32_16x16x32_bf16 v[0:3], v[176:179], v[208:211], v[0:3]
	s_setprio 0
	s_barrier
	s_add_i32 s56, 0, 0x18000
	s_add_i32 s57, 0, 0x1c000
	v_add_u32_e32 v128, s56, v163
	v_add_u32_e32 v176, s57, v163
	ds_read_b128 v[64:67], v128
	ds_read_b128 v[108:111], v128 offset:1024
	ds_read_b128 v[116:119], v128 offset:2048
	ds_read_b128 v[128:131], v128 offset:3072
	ds_read_b128 v[156:159], v176
	ds_read_b128 v[168:171], v176 offset:1024
	ds_read_b128 v[172:175], v176 offset:2048
	ds_read_b128 v[176:179], v176 offset:3072
	s_add_u32 s30, s30, 0x200000
	s_addc_u32 s31, s31, 0
	s_mov_b32 m0, s37
	v_lshl_add_u64 v[218:219], s[30:31], 0, v[144:145]
	ds_read_b128 v[180:183], v167 offset:32768
	ds_read_b128 v[184:187], v167 offset:33792
	ds_read_b128 v[188:191], v167 offset:34816
	ds_read_b128 v[192:195], v167 offset:35840
	ds_read_b128 v[196:199], v167 offset:36864
	ds_read_b128 v[200:203], v167 offset:37888
	ds_read_b128 v[204:207], v167 offset:38912
	ds_read_b128 v[208:211], v167 offset:39936
	global_load_lds_dwordx4 v[218:219], off
	v_lshl_add_u64 v[218:219], s[30:31], 0, v[146:147]
	s_mov_b32 m0, s38
	s_nop 0
	global_load_lds_dwordx4 v[218:219], off
	s_waitcnt vmcnt(8)
	s_waitcnt lgkmcnt(0)
	s_barrier
	s_setprio 1
	s_waitcnt lgkmcnt(0)
	v_mfma_f32_16x16x32_bf16 v[140:143], v[64:67], v[180:183], v[140:143]
	v_mfma_f32_16x16x32_bf16 v[136:139], v[116:119], v[180:183], v[136:139]
	v_mfma_f32_16x16x32_bf16 v[120:123], v[64:67], v[188:191], v[120:123]
	v_mfma_f32_16x16x32_bf16 v[112:115], v[116:119], v[188:191], v[112:115]
	v_mfma_f32_16x16x32_bf16 v[96:99], v[64:67], v[196:199], v[96:99]
	v_mfma_f32_16x16x32_bf16 v[92:95], v[116:119], v[196:199], v[92:95]
	v_mfma_f32_16x16x32_bf16 v[80:83], v[64:67], v[204:207], v[80:83]
	v_mfma_f32_16x16x32_bf16 v[76:79], v[116:119], v[204:207], v[76:79]
	v_mfma_f32_16x16x32_bf16 v[140:143], v[108:111], v[184:187], v[140:143]
	v_mfma_f32_16x16x32_bf16 v[136:139], v[128:131], v[184:187], v[136:139]
	v_mfma_f32_16x16x32_bf16 v[120:123], v[108:111], v[192:195], v[120:123]
	v_mfma_f32_16x16x32_bf16 v[112:115], v[128:131], v[192:195], v[112:115]
	v_mfma_f32_16x16x32_bf16 v[96:99], v[108:111], v[200:203], v[96:99]
	v_mfma_f32_16x16x32_bf16 v[92:95], v[128:131], v[200:203], v[92:95]
	v_mfma_f32_16x16x32_bf16 v[80:83], v[108:111], v[208:211], v[80:83]
	v_mfma_f32_16x16x32_bf16 v[76:79], v[128:131], v[208:211], v[76:79]
	s_setprio 0
	s_setprio 1
	v_mfma_f32_16x16x32_bf16 v[132:135], v[156:159], v[180:183], v[132:135]
	v_mfma_f32_16x16x32_bf16 v[124:127], v[172:175], v[180:183], v[124:127]
	v_mfma_f32_16x16x32_bf16 v[104:107], v[156:159], v[188:191], v[104:107]
	v_mfma_f32_16x16x32_bf16 v[100:103], v[172:175], v[188:191], v[100:103]
	v_mfma_f32_16x16x32_bf16 v[88:91], v[156:159], v[196:199], v[88:91]
	v_mfma_f32_16x16x32_bf16 v[84:87], v[172:175], v[196:199], v[84:87]
	v_mfma_f32_16x16x32_bf16 v[72:75], v[156:159], v[204:207], v[72:75]
	v_mfma_f32_16x16x32_bf16 v[68:71], v[172:175], v[204:207], v[68:71]
	v_mfma_f32_16x16x32_bf16 v[132:135], v[168:171], v[184:187], v[132:135]
	v_mfma_f32_16x16x32_bf16 v[124:127], v[176:179], v[184:187], v[124:127]
	v_mfma_f32_16x16x32_bf16 v[104:107], v[168:171], v[192:195], v[104:107]
	v_mfma_f32_16x16x32_bf16 v[100:103], v[176:179], v[192:195], v[100:103]
	v_mfma_f32_16x16x32_bf16 v[88:91], v[168:171], v[200:203], v[88:91]
	v_mfma_f32_16x16x32_bf16 v[84:87], v[176:179], v[200:203], v[84:87]
	v_mfma_f32_16x16x32_bf16 v[72:75], v[168:171], v[208:211], v[72:75]
	v_mfma_f32_16x16x32_bf16 v[68:71], v[176:179], v[208:211], v[68:71]
	s_setprio 0
	s_barrier
; #define PG8_STAGE(bufoff, gbase, voff) do { _Pragma("unroll") for (int _i = 0; _i < 2; ++_i) \
;         __builtin_amdgcn_global_load_lds((const unsigned*)((const char*)(gbase) + (voff)[_i]), (PG8_LAS unsigned*)(lds + (bufoff) + ldsw + _i * 8192), 16, 0, 0); } while (0)
; #define PG8_LDA(dst, b, h) do { _Pragma("unroll") for (int m = 0; m < 4; ++m) _Pragma("unroll") for (int k = 0; k < 2; ++k) dst[m][k] = *(const PG8_LAS bf16x8*)(lds + PG8_SA(b, h) + aoff + m * 2048 + k * 1024); } while (0)
; #define PG8_MMA(ai, bj, At, Bt) do { __builtin_amdgcn_s_setprio(1); _Pragma("unroll") for (int m = 0; m < 4; ++m) _Pragma("unroll") for (int n = 0; n < 2; ++n) _Pragma("unroll") for (int k = 0; k < 2; ++k) \
;         acc[ai][bj][m][n] = __builtin_amdgcn_mfma_f32_16x16x32_bf16(Bt[n][k], At[m][k], acc[ai][bj][m][n], 0, 0, 0); __builtin_amdgcn_s_setprio(0); } while (0)
; #define PG8_WAIT_V(n) asm volatile("s_waitcnt vmcnt(" #n ")" ::: "memory")
; #define PG8_WAIT_L(n) asm volatile("s_waitcnt lgkmcnt(" #n ")" ::: "memory")
; #define PG8_BAR __builtin_amdgcn_s_barrier()
; #define PG8_SCHED __builtin_amdgcn_sched_barrier(0)
; template <class Epi, class Sched, bool ALIGN_EPI = false, bool SP2 = false>
; __device__ __forceinline__ void gemm_phase(PG8_LAS unsigned char* lds, const Gemm g, const Sched& S, const Epi& E) {
;     ...
;             PG8_LDA(At, 1, 1); PG8_STAGE(PG8_SB(1, 0), b3, voffB); PG8_STAGE(PG8_SB(1, 1), b3 + hstep, voffB); PG8_STAGE(PG8_SA(1, 0), a3, voffA);
;             PG8_WAIT_V(8); PG8_WAIT_L(0); PG8_BAR; PG8_MMA(1, 0, At, B0); PG8_MMA(1, 1, At, B1); PG8_BAR; PG8_SCHED;
	s_add_i32 s30, s56, s34
	v_lshl_add_u64 v[160:161], v[160:161], 0, s[4:5]
	s_mov_b32 m0, s30
	ds_read_b128 v[180:183], v167 offset:49152
	ds_read_b128 v[184:187], v167 offset:50176
	ds_read_b128 v[188:191], v167 offset:51200
	ds_read_b128 v[192:195], v167 offset:52224
	ds_read_b128 v[196:199], v167 offset:53248
	ds_read_b128 v[200:203], v167 offset:54272
	ds_read_b128 v[204:207], v167 offset:55296
	ds_read_b128 v[208:211], v167 offset:56320
	global_load_lds_dwordx4 v[160:161], off
	s_add_i32 m0, s30, 0x2000
	s_add_u32 s28, s28, 0x200080
	v_lshl_add_u64 v[160:161], v[212:213], 0, s[4:5]
	s_addc_u32 s29, s29, 0
	s_add_i32 s30, s57, s34
	global_load_lds_dwordx4 v[160:161], off
	v_lshl_add_u64 v[160:161], s[28:29], 0, v[144:145]
	s_mov_b32 m0, s30
	s_nop 0
	global_load_lds_dwordx4 v[160:161], off
	v_lshl_add_u64 v[160:161], s[28:29], 0, v[146:147]
	s_add_i32 m0, s30, 0x2000
	s_nop 0
	global_load_lds_dwordx4 v[160:161], off
	v_lshl_add_u64 v[160:161], v[214:215], 0, s[4:5]
	s_mov_b32 m0, s42
	s_nop 0
	global_load_lds_dwordx4 v[160:161], off
	v_lshl_add_u64 v[160:161], v[216:217], 0, s[4:5]
	s_mov_b32 m0, s43
	s_nop 0
	global_load_lds_dwordx4 v[160:161], off
	s_waitcnt vmcnt(8)
	s_waitcnt lgkmcnt(0)
	s_barrier
	s_setprio 1
	s_waitcnt lgkmcnt(0)
	v_mfma_f32_16x16x32_bf16 v[60:63], v[64:67], v[180:183], v[60:63]
	v_mfma_f32_16x16x32_bf16 v[56:59], v[116:119], v[180:183], v[56:59]
	v_mfma_f32_16x16x32_bf16 v[44:47], v[64:67], v[188:191], v[44:47]
	v_mfma_f32_16x16x32_bf16 v[40:43], v[116:119], v[188:191], v[40:43]
	v_mfma_f32_16x16x32_bf16 v[28:31], v[64:67], v[196:199], v[28:31]
	v_mfma_f32_16x16x32_bf16 v[24:27], v[116:119], v[196:199], v[24:27]
	v_mfma_f32_16x16x32_bf16 v[12:15], v[64:67], v[204:207], v[12:15]
	v_mfma_f32_16x16x32_bf16 v[8:11], v[116:119], v[204:207], v[8:11]
	v_mfma_f32_16x16x32_bf16 v[60:63], v[108:111], v[184:187], v[60:63]
	v_mfma_f32_16x16x32_bf16 v[56:59], v[128:131], v[184:187], v[56:59]
	v_mfma_f32_16x16x32_bf16 v[44:47], v[108:111], v[192:195], v[44:47]
	v_mfma_f32_16x16x32_bf16 v[40:43], v[128:131], v[192:195], v[40:43]
	v_mfma_f32_16x16x32_bf16 v[28:31], v[108:111], v[200:203], v[28:31]
	v_mfma_f32_16x16x32_bf16 v[24:27], v[128:131], v[200:203], v[24:27]
	v_mfma_f32_16x16x32_bf16 v[12:15], v[108:111], v[208:211], v[12:15]
	v_mfma_f32_16x16x32_bf16 v[8:11], v[128:131], v[208:211], v[8:11]
	s_setprio 0
	s_setprio 1
	v_mfma_f32_16x16x32_bf16 v[52:55], v[156:159], v[180:183], v[52:55]
	v_mfma_f32_16x16x32_bf16 v[48:51], v[172:175], v[180:183], v[48:51]
	v_mfma_f32_16x16x32_bf16 v[36:39], v[156:159], v[188:191], v[36:39]
	v_mfma_f32_16x16x32_bf16 v[32:35], v[172:175], v[188:191], v[32:35]
	v_mfma_f32_16x16x32_bf16 v[20:23], v[156:159], v[196:199], v[20:23]
	v_mfma_f32_16x16x32_bf16 v[16:19], v[172:175], v[196:199], v[16:19]
	v_mfma_f32_16x16x32_bf16 v[4:7], v[156:159], v[204:207], v[4:7]
	v_mfma_f32_16x16x32_bf16 v[0:3], v[172:175], v[204:207], v[0:3]
	v_mfma_f32_16x16x32_bf16 v[52:55], v[168:171], v[184:187], v[52:55]
	v_mfma_f32_16x16x32_bf16 v[48:51], v[176:179], v[184:187], v[48:51]
	v_mfma_f32_16x16x32_bf16 v[36:39], v[168:171], v[192:195], v[36:39]
	v_mfma_f32_16x16x32_bf16 v[32:35], v[176:179], v[192:195], v[32:35]
	v_mfma_f32_16x16x32_bf16 v[20:23], v[168:171], v[200:203], v[20:23]
	v_mfma_f32_16x16x32_bf16 v[16:19], v[176:179], v[200:203], v[16:19]
	v_mfma_f32_16x16x32_bf16 v[4:7], v[168:171], v[208:211], v[4:7]
	v_mfma_f32_16x16x32_bf16 v[0:3], v[176:179], v[208:211], v[0:3]
	s_setprio 0
	s_barrier
	s_add_i32 s55, s55, 2
	s_add_u32 s26, s26, 0x100
	s_addc_u32 s27, s27, 0
	s_add_u32 s53, s53, 0x100
	s_addc_u32 s54, s54, 0
	s_cmpk_gt_u32 s55, 0x7d
